# v61 + next-tile prefetch of the first A/B lines after the last K-step barrier
# baseline (speedup 1.0000x reference)
; template <int MODE, bool SWAP, int MT>
; DI void gemm_tile(const int wv_, const Params& p, const u16* __restrict__ A, const u16* __restrict__ Bt, int brow, int bcol, char* smem, const float* gnext) {
;     ...
;   for (int t = 0; t < 32; ++t) {
;     asm volatile("s_waitcnt vmcnt(0)" ::: "memory");
;     __syncthreads();
;     if (t + 1 < 32) stage(t + 1, (t + 1) & 1);
;     const char* sA = smem + (t & 1) * 24576; const char* sB = sA + 16384;
;     bf16x8 Af[MT], Bf[4];
; #pragma unroll
;     for (int n = 0; n < 4; ++n) Bf[n] = *(const bf16x8*)(sB + (wc * 64 + n * 16 + fr) * 64 + fq * 16);
;     constexpr int MH = MT >= 2 ? MT / 2 : 1;
; #pragma unroll
;     for (int m = 0; m < MH; ++m) Af[m] = *(const bf16x8*)(sA + (wr * (16 * MT) + m * 16 + fr) * 64 + fq * 16);
;     __builtin_amdgcn_sched_barrier(0);
; #pragma unroll
;     for (int m = MH; m < MT; ++m) Af[m] = *(const bf16x8*)(sA + (wr * (16 * MT) + m * 16 + fr) * 64 + fq * 16);
; #pragma unroll
;     for (int m = 0; m < MH; ++m)
; #pragma unroll
;       for (int n = 0; n < 4; ++n)
;         acc[m][n] = SWAP ? __builtin_amdgcn_mfma_f32_16x16x32_bf16(Bf[n], Af[m], acc[m][n], 0, 0, 0)
;                          : __builtin_amdgcn_mfma_f32_16x16x32_bf16(Af[m], Bf[n], acc[m][n], 0, 0, 0);
;     __builtin_amdgcn_sched_barrier(0);
; #pragma unroll
;     for (int m = MH; m < MT; ++m)
; #pragma unroll
;       for (int n = 0; n < 4; ++n)
;         acc[m][n] = SWAP ? __builtin_amdgcn_mfma_f32_16x16x32_bf16(Bf[n], Af[m], acc[m][n], 0, 0, 0)
;                          : __builtin_amdgcn_mfma_f32_16x16x32_bf16(Af[m], Bf[n], acc[m][n], 0, 0, 0);
;     ...
;       } else {
;         const float rs = rowscale(p.ss, R);
; #pragma unroll
;         for (int n = 0; n < 4; ++n) { acc[m][n][0] *= rs; acc[m][n][1] *= rs; acc[m][n][2] *= rs; acc[m][n][3] *= rs; }
;         if (MODE == 0 && bcol >= 512 && bcol < 1536) {
;           int b = R / P, pos = R - b * P;
;           u16* dstb = (bcol < 1024 ? p.kc : p.vc);
; #pragma unroll
;           for (int n = 0; n < 4; ++n) {
;             int cc = (bcol & 511) + wc * 64 + n * 16 + fq * 4;
;             uint2 o; o.x = pack2(acc[m][n][0], acc[m][n][1]); o.y = pack2(acc[m][n][2], acc[m][n][3]);
;             *(uint2*)(dstb + ((size_t)((b * 8 + (cc >> 6)) * P + pos)) * 64 + (cc & 63)) = o;
;           }
;         } else {
;           const int LD = MODE == 0 ? LD_AB : LD_CD;
.Lpp_exit_1:
	s_add_i32 s98, s14, s7
	s_cmp_lt_i32 s98, s8
	s_cselect_b32 s98, s98, s14
	s_lshr_b32 s99, s98, 2
	s_mul_i32 s99, s99, 9363
	s_lshr_b32 s99, s99, 16
	s_mul_i32 s100, s99, 28
	s_sub_i32 s100, s98, s100
	s_lshl_b32 s99, s99, 8
	s_sub_i32 s98, s99, s18
	s_add_i32 s98, s98, -1
	s_ashr_i32 s99, s98, 31
	s_lshl_b64 s[98:99], s[98:99], 11
	s_lshl_b32 s100, s100, 7
	s_sub_i32 s100, s100, s15
	s_add_i32 s100, s100, -1
	s_ashr_i32 s101, s100, 31
	s_lshl_b64 s[100:101], s[100:101], 11
	v_lshl_add_u64 v[112:113], v[0:1], 0, s[98:99]
	v_lshl_add_u64 v[114:115], v[68:69], 0, s[98:99]
	v_lshl_add_u64 v[116:117], v[70:71], 0, s[100:101]
	v_add_u32_e32 v0, v77, v79
	v_add_u32_e32 v1, v77, v78
	s_waitcnt vmcnt(0)
	s_waitcnt vmcnt(0)
	s_barrier
	global_load_dword v108, v[112:113], off
	global_load_dword v109, v[114:115], off
	global_load_dword v110, v[116:117], off
	ds_read_b128 v[68:71], v0 offset:25600
	ds_read_b128 v[80:83], v0 offset:24576
	ds_read_b128 v[76:79], v1 offset:44032
	ds_read_b128 v[84:87], v1 offset:43008
	ds_read_b128 v[88:91], v1 offset:41984
	ds_read_b128 v[92:95], v1 offset:40960
	s_waitcnt lgkmcnt(0)
	v_mfma_f32_16x16x32_bf16 v[64:67], v[92:95], v[80:83], v[64:67]
	v_mfma_f32_16x16x32_bf16 v[60:63], v[88:91], v[80:83], v[60:63]
	v_mfma_f32_16x16x32_bf16 v[56:59], v[84:87], v[80:83], v[56:59]
	v_mfma_f32_16x16x32_bf16 v[52:55], v[76:79], v[80:83], v[52:55]
	ds_read_b128 v[80:83], v0 offset:26624
	ds_read_b128 v[96:99], v0 offset:27648
	v_mfma_f32_16x16x32_bf16 v[48:51], v[92:95], v[68:71], v[48:51]
	v_mfma_f32_16x16x32_bf16 v[40:43], v[88:91], v[68:71], v[40:43]
	v_mfma_f32_16x16x32_bf16 v[36:39], v[84:87], v[68:71], v[36:39]
	v_mfma_f32_16x16x32_bf16 v[44:47], v[76:79], v[68:71], v[44:47]
	v_or_b32_e32 v0, s18, v74
	v_lshl_add_u32 v68, v73, 6, v0
	v_lshlrev_b32_e32 v0, 6, v72
	v_lshlrev_b32_e32 v1, 2, v75
	v_ashrrev_i32_e32 v69, 31, v68
	v_or3_b32 v70, v0, v1, s15
	v_lshlrev_b64 v[0:1], 6, v[68:69]
	v_lshl_add_u64 v[0:1], s[90:91], 0, v[0:1]
	s_waitcnt lgkmcnt(1)
	v_mfma_f32_16x16x32_bf16 v[32:35], v[92:95], v[80:83], v[32:35]
	s_waitcnt lgkmcnt(0)
	s_barrier
	v_mfma_f32_16x16x32_bf16 v[28:31], v[88:91], v[80:83], v[28:31]
	v_mov_b32_e32 v69, 0x358637bd
	v_ashrrev_i32_e32 v71, 31, v70
	v_mfma_f32_16x16x32_bf16 v[24:27], v[84:87], v[80:83], v[24:27]
	v_mfma_f32_16x16x32_bf16 v[20:23], v[76:79], v[80:83], v[20:23]
	v_mfma_f32_16x16x32_bf16 v[8:11], v[84:87], v[96:99], v[8:11]
	v_mfma_f32_16x16x32_bf16 v[4:7], v[76:79], v[96:99], v[4:7]
	global_load_dwordx4 v[72:75], v[0:1], off offset:32
	global_load_dwordx4 v[76:79], v[0:1], off offset:16
	global_load_dwordx4 v[80:83], v[0:1], off
	global_load_dwordx4 v[84:87], v[0:1], off offset:48
	s_waitcnt vmcnt(3)
	v_mov_b32_e32 v2, v73
	v_mfma_f32_16x16x32_bf16 v[12:15], v[88:91], v[96:99], v[12:15]
	s_waitcnt vmcnt(1)
	v_mov_b32_e32 v0, v81
	v_mov_b32_e32 v1, v82
	v_mov_b32_e32 v88, v77
	v_mov_b32_e32 v89, v78
	v_mov_b32_e32 v81, v83
	v_mov_b32_e32 v77, v79
	v_pk_add_f32 v[0:1], v[0:1], v[80:81]
	v_pk_add_f32 v[76:77], v[88:89], v[76:77]
	v_pk_add_f32 v[72:73], v[72:73], v[2:3]
	v_mov_b32_e32 v2, v75
	v_pk_add_f32 v[0:1], v[0:1], v[0:1] op_sel:[0,1] op_sel_hi:[1,0]
	v_pk_add_f32 v[76:77], v[76:77], v[76:77] op_sel:[0,1] op_sel_hi:[1,0]
	v_pk_add_f32 v[74:75], v[74:75], v[2:3]
	s_waitcnt vmcnt(0)
	v_mov_b32_e32 v1, v84
	v_mov_b32_e32 v77, v85
	v_mov_b32_e32 v73, v86
	v_mov_b32_e32 v75, v87
	v_pk_add_f32 v[0:1], v[0:1], v[76:77]
	v_pk_add_f32 v[72:73], v[72:73], v[74:75]
	v_mfma_f32_16x16x32_bf16 v[16:19], v[92:95], v[96:99], v[16:19]
	v_add_f32_e64 v0, v0, v72
	v_add_f32_e64 v1, v1, v73
	v_add_f32_e32 v0, v0, v1
	v_fmamk_f32 v0, v0, 0x3a800000, v69
	v_cmp_gt_f32_e32 vcc, s96, v0
	v_mul_f32_e32 v1, 0x4b800000, v0
	s_nop 0
	v_cndmask_b32_e32 v0, v0, v1, vcc
	v_rsq_f32_e32 v0, v0
	s_nop 0
	v_mul_f32_e32 v1, 0x45800000, v0
	v_cndmask_b32_e32 v0, v0, v1, vcc
	v_pk_mul_f32 v[72:73], v[64:65], v[0:1] op_sel_hi:[1,0]
	v_pk_mul_f32 v[66:67], v[66:67], v[0:1] op_sel_hi:[1,0]
	v_pk_mul_f32 v[64:65], v[60:61], v[0:1] op_sel_hi:[1,0]
	v_pk_mul_f32 v[62:63], v[62:63], v[0:1] op_sel_hi:[1,0]
	v_pk_mul_f32 v[60:61], v[56:57], v[0:1] op_sel_hi:[1,0]
	v_pk_mul_f32 v[58:59], v[58:59], v[0:1] op_sel_hi:[1,0]
	v_pk_mul_f32 v[56:57], v[52:53], v[0:1] op_sel_hi:[1,0]
	v_pk_mul_f32 v[54:55], v[54:55], v[0:1] op_sel_hi:[1,0]
	v_mov_b64_e32 v[0:1], s[68:69]
	v_mad_i64_i32 v[74:75], s[0:1], v68, s34, v[0:1]
	v_lshlrev_b64 v[52:53], 1, v[70:71]
	v_cvt_pk_bf16_f32 v56, v56, v57
	v_cvt_pk_bf16_f32 v57, v54, v55
	v_or_b32_e32 v54, 16, v68
	v_cvt_pk_bf16_f32 v72, v72, v73
	v_cvt_pk_bf16_f32 v73, v66, v67
	v_lshl_add_u64 v[66:67], v[74:75], 0, v[52:53]
	v_ashrrev_i32_e32 v55, 31, v54
	v_cvt_pk_bf16_f32 v64, v64, v65
	v_cvt_pk_bf16_f32 v65, v62, v63
	v_cvt_pk_bf16_f32 v60, v60, v61
	v_cvt_pk_bf16_f32 v61, v58, v59
	global_store_dwordx2 v[66:67], v[56:57], off offset:96
	v_lshlrev_b64 v[56:57], 6, v[54:55]
	global_store_dwordx2 v[66:67], v[72:73], off
	global_store_dwordx2 v[66:67], v[64:65], off offset:32
	global_store_dwordx2 v[66:67], v[60:61], off offset:64
	v_lshl_add_u64 v[70:71], s[90:91], 0, v[56:57]
	global_load_dwordx4 v[56:59], v[70:71], off offset:32
	global_load_dwordx4 v[60:63], v[70:71], off offset:16
	global_load_dwordx4 v[64:67], v[70:71], off
	s_nop 0
	global_load_dwordx4 v[70:73], v[70:71], off offset:48
	s_waitcnt vmcnt(3)
	v_mov_b32_e32 v2, v57
	s_waitcnt vmcnt(2)
	v_mov_b32_e32 v76, v61
	s_waitcnt vmcnt(1)
; DI unsigned pack2(float a, float b) { f32x2_t v = {a, b}; return __builtin_bit_cast(unsigned, __builtin_convertvector(v, bf16x2_t)); }
; template <int MODE, bool SWAP, int MT>
; DI void gemm_tile(const int wv_, const Params& p, const u16* __restrict__ A, const u16* __restrict__ Bt, int brow, int bcol, char* smem, const float* gnext) {
;     ...
;       } else {
;         const float rs = rowscale(p.ss, R);
; #pragma unroll
;         for (int n = 0; n < 4; ++n) { acc[m][n][0] *= rs; acc[m][n][1] *= rs; acc[m][n][2] *= rs; acc[m][n][3] *= rs; }
;         if (MODE == 0 && bcol >= 512 && bcol < 1536) {
;           int b = R / P, pos = R - b * P;
;           u16* dstb = (bcol < 1024 ? p.kc : p.vc);
; #pragma unroll
;           for (int n = 0; n < 4; ++n) {
;             int cc = (bcol & 511) + wc * 64 + n * 16 + fq * 4;
;             uint2 o; o.x = pack2(acc[m][n][0], acc[m][n][1]); o.y = pack2(acc[m][n][2], acc[m][n][3]);
;             *(uint2*)(dstb + ((size_t)((b * 8 + (cc >> 6)) * P + pos)) * 64 + (cc & 63)) = o;
;           }
;         } else {
;           const int LD = MODE == 0 ? LD_AB : LD_CD;
;           u16* pr = p.proj + (size_t)R * LD;
; #pragma unroll
;           for (int n = 0; n < 4; ++n) {
;             int col = bcol + wc * 64 + n * 16 + fq * 4;
;             if (MODE == 1 || col < 4184) {
;               uint2 o; o.x = pack2(acc[m][n][0], acc[m][n][1]); o.y = pack2(acc[m][n][2], acc[m][n][3]);
;               int pcol = (MODE == 0 && col >= 1536) ? col - 1024 : col;
;               *(uint2*)(pr + pcol) = o;
;               if (MODE == 0 && col >= 2560 && col < 2624) *(uint2*)(p.ikc + (size_t)R * 64 + (col - 2560)) = o;
;             }
;           }
	v_mov_b32_e32 v74, v65
	v_mov_b32_e32 v75, v66
	v_mov_b32_e32 v77, v62
	v_mov_b32_e32 v65, v67
	v_mov_b32_e32 v61, v63
	v_pk_add_f32 v[64:65], v[74:75], v[64:65]
	v_pk_add_f32 v[60:61], v[76:77], v[60:61]
	v_pk_add_f32 v[56:57], v[56:57], v[2:3]
	v_mov_b32_e32 v2, v59
	v_pk_add_f32 v[64:65], v[64:65], v[64:65] op_sel:[0,1] op_sel_hi:[1,0]
	v_pk_add_f32 v[60:61], v[60:61], v[60:61] op_sel:[0,1] op_sel_hi:[1,0]
	v_pk_add_f32 v[58:59], v[58:59], v[2:3]
	s_waitcnt vmcnt(0)
	v_mov_b32_e32 v65, v70
	v_mov_b32_e32 v61, v71
	v_mov_b32_e32 v57, v72
	v_mov_b32_e32 v59, v73
	v_pk_add_f32 v[60:61], v[64:65], v[60:61]
	v_pk_add_f32 v[56:57], v[56:57], v[58:59]
	s_nop 0
	v_pk_add_f32 v[56:57], v[60:61], v[56:57]
	s_nop 0
	v_add_f32_e32 v2, v56, v57
	v_fmamk_f32 v2, v2, 0x3a800000, v69
	v_cmp_gt_f32_e32 vcc, s96, v2
	v_mul_f32_e32 v55, 0x4b800000, v2
	s_nop 0
	v_cndmask_b32_e32 v2, v2, v55, vcc
	v_rsq_f32_e32 v2, v2
	s_nop 0
	v_mul_f32_e32 v55, 0x45800000, v2
	v_cndmask_b32_e32 v2, v2, v55, vcc
	v_pk_mul_f32 v[48:49], v[48:49], v[2:3] op_sel_hi:[1,0]
	v_pk_mul_f32 v[50:51], v[50:51], v[2:3] op_sel_hi:[1,0]
	v_pk_mul_f32 v[36:37], v[36:37], v[2:3] op_sel_hi:[1,0]
	v_pk_mul_f32 v[38:39], v[38:39], v[2:3] op_sel_hi:[1,0]
	v_mad_i64_i32 v[54:55], s[0:1], v54, s34, v[0:1]
	v_pk_mul_f32 v[44:45], v[44:45], v[2:3] op_sel_hi:[1,0]
	v_cvt_pk_bf16_f32 v48, v48, v49
	v_cvt_pk_bf16_f32 v49, v50, v51
	v_lshl_add_u64 v[50:51], v[54:55], 0, v[52:53]
	v_cvt_pk_bf16_f32 v36, v36, v37
	v_cvt_pk_bf16_f32 v37, v38, v39
	v_pk_mul_f32 v[46:47], v[46:47], v[2:3] op_sel_hi:[1,0]
	global_store_dwordx2 v[50:51], v[36:37], off offset:64
	v_cvt_pk_bf16_f32 v36, v44, v45
	v_or_b32_e32 v44, 32, v68
	v_pk_mul_f32 v[40:41], v[40:41], v[2:3] op_sel_hi:[1,0]
	v_pk_mul_f32 v[42:43], v[42:43], v[2:3] op_sel_hi:[1,0]
	v_cvt_pk_bf16_f32 v37, v46, v47
	v_ashrrev_i32_e32 v45, 31, v44
	v_cvt_pk_bf16_f32 v40, v40, v41
	v_cvt_pk_bf16_f32 v41, v42, v43
	global_store_dwordx2 v[50:51], v[36:37], off offset:96
	v_lshlrev_b64 v[36:37], 6, v[44:45]
	global_store_dwordx2 v[50:51], v[48:49], off
	global_store_dwordx2 v[50:51], v[40:41], off offset:32
	v_lshl_add_u64 v[50:51], s[90:91], 0, v[36:37]
	global_load_dwordx4 v[36:39], v[50:51], off offset:32
	global_load_dwordx4 v[40:43], v[50:51], off offset:16
	global_load_dwordx4 v[46:49], v[50:51], off
	global_load_dwordx4 v[54:57], v[50:51], off offset:48
	s_waitcnt vmcnt(3)
	v_mov_b32_e32 v2, v37
	s_waitcnt vmcnt(2)
	v_mov_b32_e32 v58, v41
	s_waitcnt vmcnt(1)
	v_mov_b32_e32 v50, v47
	v_mov_b32_e32 v51, v48
	v_mov_b32_e32 v59, v42
	v_mov_b32_e32 v47, v49
	v_mov_b32_e32 v41, v43
	v_pk_add_f32 v[46:47], v[50:51], v[46:47]
	v_pk_add_f32 v[40:41], v[58:59], v[40:41]
	v_pk_add_f32 v[36:37], v[36:37], v[2:3]
	v_mov_b32_e32 v2, v39
	v_pk_add_f32 v[46:47], v[46:47], v[46:47] op_sel:[0,1] op_sel_hi:[1,0]
	v_pk_add_f32 v[40:41], v[40:41], v[40:41] op_sel:[0,1] op_sel_hi:[1,0]
	v_pk_add_f32 v[38:39], v[38:39], v[2:3]
	s_waitcnt vmcnt(0)
	v_mov_b32_e32 v47, v54
	v_mov_b32_e32 v41, v55
	v_mov_b32_e32 v37, v56
	v_mov_b32_e32 v39, v57
	v_pk_add_f32 v[40:41], v[46:47], v[40:41]
	v_pk_add_f32 v[36:37], v[36:37], v[38:39]
	s_nop 0
	v_pk_add_f32 v[36:37], v[40:41], v[36:37]
	s_nop 0
	v_add_f32_e32 v2, v36, v37
	v_fmamk_f32 v2, v2, 0x3a800000, v69
	v_cmp_gt_f32_e32 vcc, s96, v2
	v_mul_f32_e32 v36, 0x4b800000, v2
	s_nop 0
	v_cndmask_b32_e32 v2, v2, v36, vcc
	v_rsq_f32_e32 v2, v2
	s_nop 0
	v_mul_f32_e32 v36, 0x45800000, v2
	v_cndmask_b32_e32 v2, v2, v36, vcc
	v_pk_mul_f32 v[32:33], v[32:33], v[2:3] op_sel_hi:[1,0]
	v_pk_mul_f32 v[34:35], v[34:35], v[2:3] op_sel_hi:[1,0]
	v_pk_mul_f32 v[28:29], v[28:29], v[2:3] op_sel_hi:[1,0]
	v_pk_mul_f32 v[30:31], v[30:31], v[2:3] op_sel_hi:[1,0]
	v_mad_i64_i32 v[36:37], s[0:1], v44, s34, v[0:1]
	v_cvt_pk_bf16_f32 v32, v32, v33
	v_cvt_pk_bf16_f32 v33, v34, v35
	v_lshl_add_u64 v[34:35], v[36:37], 0, v[52:53]
	v_cvt_pk_bf16_f32 v28, v28, v29
	v_cvt_pk_bf16_f32 v29, v30, v31
	v_pk_mul_f32 v[20:21], v[20:21], v[2:3] op_sel_hi:[1,0]
	v_pk_mul_f32 v[22:23], v[22:23], v[2:3] op_sel_hi:[1,0]
	global_store_dwordx2 v[34:35], v[28:29], off offset:32
	v_or_b32_e32 v28, 48, v68
	v_pk_mul_f32 v[24:25], v[24:25], v[2:3] op_sel_hi:[1,0]
	v_pk_mul_f32 v[26:27], v[26:27], v[2:3] op_sel_hi:[1,0]
	v_cvt_pk_bf16_f32 v20, v20, v21
	v_cvt_pk_bf16_f32 v21, v22, v23
	v_ashrrev_i32_e32 v29, 31, v28
	v_cvt_pk_bf16_f32 v24, v24, v25
	v_cvt_pk_bf16_f32 v25, v26, v27
	global_store_dwordx2 v[34:35], v[20:21], off offset:96
	v_lshlrev_b64 v[20:21], 6, v[28:29]
	global_store_dwordx2 v[34:35], v[32:33], off
	global_store_dwordx2 v[34:35], v[24:25], off offset:64
	v_lshl_add_u64 v[34:35], s[90:91], 0, v[20:21]
	global_load_dwordx4 v[20:23], v[34:35], off offset:32
	global_load_dwordx4 v[24:27], v[34:35], off offset:16
	global_load_dwordx4 v[30:33], v[34:35], off
	s_nop 0
	global_load_dwordx4 v[34:37], v[34:35], off offset:48
	v_mad_i64_i32 v[0:1], s[0:1], v28, s34, v[0:1]
	v_lshl_add_u64 v[0:1], v[0:1], 0, v[52:53]
	s_mov_b64 s[0:1], 0x60
	s_waitcnt vmcnt(3)
	v_mov_b32_e32 v2, v21
	s_waitcnt vmcnt(2)
	v_mov_b32_e32 v40, v25
	s_waitcnt vmcnt(1)
	v_mov_b32_e32 v38, v31
	v_mov_b32_e32 v39, v32
	v_mov_b32_e32 v41, v26
	v_mov_b32_e32 v31, v33
	v_mov_b32_e32 v25, v27
	v_pk_add_f32 v[30:31], v[38:39], v[30:31]
	v_pk_add_f32 v[24:25], v[40:41], v[24:25]
	v_pk_add_f32 v[20:21], v[20:21], v[2:3]
	v_mov_b32_e32 v2, v23
	v_pk_add_f32 v[30:31], v[30:31], v[30:31] op_sel:[0,1] op_sel_hi:[1,0]
	v_pk_add_f32 v[24:25], v[24:25], v[24:25] op_sel:[0,1] op_sel_hi:[1,0]
	v_pk_add_f32 v[22:23], v[22:23], v[2:3]
	s_waitcnt vmcnt(0)
	v_mov_b32_e32 v31, v34
	v_mov_b32_e32 v25, v35
	v_mov_b32_e32 v21, v36
	v_mov_b32_e32 v23, v37
	v_pk_add_f32 v[24:25], v[30:31], v[24:25]
	v_pk_add_f32 v[20:21], v[20:21], v[22:23]
	s_nop 0
	v_pk_add_f32 v[20:21], v[24:25], v[20:21]
	s_nop 0
	v_add_f32_e32 v2, v20, v21
	v_fmamk_f32 v2, v2, 0x3a800000, v69
	v_cmp_gt_f32_e32 vcc, s96, v2
	v_mul_f32_e32 v20, 0x4b800000, v2
	s_nop 0
	v_cndmask_b32_e32 v2, v2, v20, vcc
	v_rsq_f32_e32 v2, v2
	s_nop 0
	v_mul_f32_e32 v20, 0x45800000, v2
	v_cndmask_b32_e32 v2, v2, v20, vcc
	v_pk_mul_f32 v[16:17], v[16:17], v[2:3] op_sel_hi:[1,0]
	v_pk_mul_f32 v[18:19], v[18:19], v[2:3] op_sel_hi:[1,0]
	v_pk_mul_f32 v[12:13], v[12:13], v[2:3] op_sel_hi:[1,0]
	v_pk_mul_f32 v[14:15], v[14:15], v[2:3] op_sel_hi:[1,0]
	v_pk_mul_f32 v[20:21], v[4:5], v[2:3] op_sel_hi:[1,0]
	v_pk_mul_f32 v[4:5], v[6:7], v[2:3] op_sel_hi:[1,0]
	v_cvt_pk_bf16_f32 v6, v16, v17
	v_cvt_pk_bf16_f32 v7, v18, v19
	v_pk_mul_f32 v[8:9], v[8:9], v[2:3] op_sel_hi:[1,0]
	v_pk_mul_f32 v[10:11], v[10:11], v[2:3] op_sel_hi:[1,0]
	global_store_dwordx2 v[0:1], v[6:7], off
	v_cvt_pk_bf16_f32 v6, v12, v13
	v_cvt_pk_bf16_f32 v7, v14, v15
	global_store_dwordx2 v[0:1], v[6:7], off offset:32
	v_cvt_pk_bf16_f32 v6, v8, v9
	v_cvt_pk_bf16_f32 v7, v10, v11
	global_store_dwordx2 v[0:1], v[6:7], off offset:64
	v_cvt_pk_bf16_f32 v2, v20, v21
	v_lshl_add_u64 v[6:7], v[0:1], 0, s[0:1]
	s_mov_b64 s[0:1], 0
	global_store_dword v[0:1], v2, off offset:96

; DI unsigned pack2(float a, float b) { f32x2_t v = {a, b}; return __builtin_bit_cast(unsigned, __builtin_convertvector(v, bf16x2_t)); }
; template <int MODE, bool SWAP, int MT>
; DI void gemm_tile(const int wv_, const Params& p, const u16* __restrict__ A, const u16* __restrict__ Bt, int brow, int bcol, char* smem, const float* gnext) {
;     ...
;   for (int t = 0; t < 32; ++t) {
;     asm volatile("s_waitcnt vmcnt(0)" ::: "memory");
;     __syncthreads();
;     if (t + 1 < 32) stage(t + 1, (t + 1) & 1);
;     const char* sA = smem + (t & 1) * 24576; const char* sB = sA + 16384;
;     bf16x8 Af[MT], Bf[4];
; #pragma unroll
;     for (int n = 0; n < 4; ++n) Bf[n] = *(const bf16x8*)(sB + (wc * 64 + n * 16 + fr) * 64 + fq * 16);
;     constexpr int MH = MT >= 2 ? MT / 2 : 1;
; #pragma unroll
;     for (int m = 0; m < MH; ++m) Af[m] = *(const bf16x8*)(sA + (wr * (16 * MT) + m * 16 + fr) * 64 + fq * 16);
;     __builtin_amdgcn_sched_barrier(0);
; #pragma unroll
;     for (int m = MH; m < MT; ++m) Af[m] = *(const bf16x8*)(sA + (wr * (16 * MT) + m * 16 + fr) * 64 + fq * 16);
; #pragma unroll
;     for (int m = 0; m < MH; ++m)
; #pragma unroll
;       for (int n = 0; n < 4; ++n)
;         acc[m][n] = SWAP ? __builtin_amdgcn_mfma_f32_16x16x32_bf16(Bf[n], Af[m], acc[m][n], 0, 0, 0)
;                          : __builtin_amdgcn_mfma_f32_16x16x32_bf16(Af[m], Bf[n], acc[m][n], 0, 0, 0);
;     __builtin_amdgcn_sched_barrier(0);
; #pragma unroll
;     for (int m = MH; m < MT; ++m)
; #pragma unroll
;       for (int n = 0; n < 4; ++n)
;         acc[m][n] = SWAP ? __builtin_amdgcn_mfma_f32_16x16x32_bf16(Bf[n], Af[m], acc[m][n], 0, 0, 0)
;                          : __builtin_amdgcn_mfma_f32_16x16x32_bf16(Af[m], Bf[n], acc[m][n], 0, 0, 0);
;     ...
; #pragma unroll
;     for (int m = 0; m < MT; ++m) {
;       int R = brow + wr * (16 * MT) + m * 16 + fq * 4;
;       int b = R / P, pos = R - b * P;
;       const float rs0 = rowscale(p.ss, R), rs1 = rowscale(p.ss, R + 1), rs2 = rowscale(p.ss, R + 2), rs3 = rowscale(p.ss, R + 3);
; #pragma unroll
;       for (int n = 0; n < 4; ++n) {
;         int col = bcol + wc * 64 + n * 16 + fr - 2560;
;         uint2 o; o.x = pack2(acc[m][n][0] * rs0, acc[m][n][1] * rs1); o.y = pack2(acc[m][n][2] * rs2, acc[m][n][3] * rs3);
;         *(uint2*)(p.vt + ((size_t)(b * 512 + col)) * P + pos) = o;
;       }
;     }
.Lpp_exit_2:
	s_add_i32 s98, s14, s7
	s_cmp_lt_i32 s98, s8
	s_cselect_b32 s98, s98, s14
	s_lshr_b32 s99, s98, 2
	s_mul_i32 s99, s99, 9363
	s_lshr_b32 s99, s99, 16
	s_mul_i32 s100, s99, 28
	s_sub_i32 s100, s98, s100
	s_lshl_b32 s99, s99, 8
	s_sub_i32 s98, s99, s18
	s_add_i32 s98, s98, -1
	s_ashr_i32 s99, s98, 31
	s_lshl_b64 s[98:99], s[98:99], 11
	s_lshl_b32 s100, s100, 7
	s_sub_i32 s100, s100, s15
	s_add_i32 s100, s100, -1
	s_ashr_i32 s101, s100, 31
	s_lshl_b64 s[100:101], s[100:101], 11
	v_lshl_add_u64 v[112:113], v[0:1], 0, s[98:99]
	v_lshl_add_u64 v[114:115], v[68:69], 0, s[98:99]
	v_lshl_add_u64 v[116:117], v[70:71], 0, s[100:101]
	v_add_u32_e32 v0, v77, v79
	v_add_u32_e32 v1, v77, v78
	s_waitcnt vmcnt(0)
	s_waitcnt vmcnt(0)
	s_barrier
	global_load_dword v108, v[112:113], off
	global_load_dword v109, v[114:115], off
	global_load_dword v110, v[116:117], off
	ds_read_b128 v[68:71], v0 offset:25600
	ds_read_b128 v[80:83], v0 offset:24576
	ds_read_b128 v[76:79], v1 offset:44032
	ds_read_b128 v[84:87], v1 offset:43008
	ds_read_b128 v[88:91], v1 offset:41984
	ds_read_b128 v[92:95], v1 offset:40960
	s_waitcnt lgkmcnt(0)
	v_mfma_f32_16x16x32_bf16 v[64:67], v[80:83], v[92:95], v[64:67]
	v_mfma_f32_16x16x32_bf16 v[60:63], v[80:83], v[88:91], v[60:63]
	v_mfma_f32_16x16x32_bf16 v[56:59], v[80:83], v[84:87], v[56:59]
	v_mfma_f32_16x16x32_bf16 v[52:55], v[80:83], v[76:79], v[52:55]
	ds_read_b128 v[80:83], v0 offset:26624
	ds_read_b128 v[96:99], v0 offset:27648
	v_mfma_f32_16x16x32_bf16 v[48:51], v[68:71], v[92:95], v[48:51]
	v_mfma_f32_16x16x32_bf16 v[44:47], v[68:71], v[88:91], v[44:47]
	v_mfma_f32_16x16x32_bf16 v[40:43], v[68:71], v[84:87], v[40:43]
	v_mfma_f32_16x16x32_bf16 v[36:39], v[68:71], v[76:79], v[36:39]
	v_lshl_add_u32 v0, v74, 6, s18
	s_waitcnt lgkmcnt(0)
	v_mfma_f32_16x16x32_bf16 v[16:19], v[96:99], v[92:95], v[16:19]
	s_addk_i32 s15, 0xf600
	s_movk_i32 s19, 0xdf80
	v_mfma_f32_16x16x32_bf16 v[12:15], v[96:99], v[88:91], v[12:15]
	s_barrier
	s_mov_b32 s0, 0x358637bd
	v_mfma_f32_16x16x32_bf16 v[8:11], v[96:99], v[84:87], v[8:11]
	s_mov_b32 s18, 0x3a800000
	s_mov_b32 s20, 0x45800000
	v_mfma_f32_16x16x32_bf16 v[4:7], v[96:99], v[76:79], v[4:7]
	v_lshl_or_b32 v96, v75, 2, v0
	v_lshlrev_b32_e32 v0, 6, v72
	v_or3_b32 v2, v0, s15, v73
	s_mov_b32 s15, 0x7e07e07f
	v_mul_hi_i32 v0, v96, s15
	v_lshrrev_b32_e32 v1, 31, v0
	v_ashrrev_i32_e32 v0, 12, v0
	v_ashrrev_i32_e32 v97, 31, v96
	v_or_b32_e32 v68, 2, v96
	v_add_u32_e32 v70, v0, v1
	v_lshlrev_b64 v[0:1], 6, v[96:97]
	v_ashrrev_i32_e32 v69, 31, v68
	v_lshl_add_u64 v[0:1], s[90:91], 0, v[0:1]
	v_lshlrev_b64 v[68:69], 6, v[68:69]
	v_mfma_f32_16x16x32_bf16 v[32:35], v[80:83], v[92:95], v[32:35]
	v_mad_i32_i24 v98, v70, s19, v96
	v_lshl_add_u64 v[102:103], s[90:91], 0, v[68:69]
	v_lshl_or_b32 v97, v70, 9, v2
	v_mfma_f32_16x16x32_bf16 v[28:31], v[80:83], v[88:91], v[28:31]
	v_ashrrev_i32_e32 v99, 31, v98
	v_mfma_f32_16x16x32_bf16 v[24:27], v[80:83], v[84:87], v[24:27]
	v_mfma_f32_16x16x32_bf16 v[20:23], v[80:83], v[76:79], v[20:23]
	global_load_dwordx4 v[68:71], v[0:1], off offset:112
	global_load_dwordx4 v[72:75], v[0:1], off offset:48
	global_load_dwordx4 v[76:79], v[0:1], off offset:96
	global_load_dwordx4 v[80:83], v[0:1], off offset:32
	global_load_dwordx4 v[84:87], v[0:1], off offset:80
	global_load_dwordx4 v[88:91], v[0:1], off offset:16
	global_load_dwordx4 v[92:95], v[0:1], off offset:64
	global_load_dwordx4 v[104:107], v[0:1], off
	s_waitcnt vmcnt(1)
	v_mov_b32_e32 v1, v92
	s_waitcnt vmcnt(0)
	v_mov_b32_e32 v0, v104
	v_mov_b32_e32 v92, v105
	v_pk_add_f32 v[0:1], v[0:1], v[92:93]
	v_mov_b32_e32 v92, v106
	v_mov_b32_e32 v93, v94
	v_mov_b32_e32 v94, v107
	v_pk_add_f32 v[92:93], v[92:93], v[94:95]
	s_nop 0
	v_pk_add_f32 v[0:1], v[0:1], v[92:93]
	v_mov_b32_e32 v92, v88
	v_mov_b32_e32 v93, v84
	v_mov_b32_e32 v84, v89
	v_mov_b32_e32 v88, v90
	v_mov_b32_e32 v89, v86
	v_mov_b32_e32 v86, v91
	v_pk_add_f32 v[84:85], v[92:93], v[84:85]
	v_pk_add_f32 v[86:87], v[88:89], v[86:87]
	s_nop 0
	v_pk_add_f32 v[84:85], v[84:85], v[86:87]
	s_nop 0
	v_pk_add_f32 v[0:1], v[0:1], v[84:85]
	v_mov_b32_e32 v84, v80
	v_mov_b32_e32 v85, v76
	v_mov_b32_e32 v76, v81
	v_mov_b32_e32 v80, v82
	v_mov_b32_e32 v81, v78
	v_mov_b32_e32 v78, v83
	v_pk_add_f32 v[76:77], v[84:85], v[76:77]
	v_pk_add_f32 v[78:79], v[80:81], v[78:79]
	s_nop 0
	v_pk_add_f32 v[76:77], v[76:77], v[78:79]
	s_nop 0
	v_pk_add_f32 v[0:1], v[0:1], v[76:77]
	v_mov_b32_e32 v76, v72
	v_mov_b32_e32 v77, v68
	v_mov_b32_e32 v68, v73
	v_mov_b32_e32 v72, v74
	v_mov_b32_e32 v73, v70
	v_mov_b32_e32 v70, v75
	v_pk_add_f32 v[68:69], v[76:77], v[68:69]
	v_pk_add_f32 v[70:71], v[72:73], v[70:71]
	s_nop 0
	v_pk_add_f32 v[68:69], v[68:69], v[70:71]
	s_nop 0
	v_pk_add_f32 v[68:69], v[0:1], v[68:69]
	v_mov_b64_e32 v[0:1], s[0:1]
	v_pk_fma_f32 v[68:69], v[68:69], s[18:19], v[0:1] op_sel_hi:[1,0,0]
	s_nop 0
	v_mul_f32_e32 v70, 0x4b800000, v68
	v_cmp_gt_f32_e64 s[0:1], s96, v68
	v_cmp_gt_f32_e32 vcc, s96, v69
	s_nop 0
	v_cndmask_b32_e64 v68, v68, v70, s[0:1]
	v_mul_f32_e32 v70, 0x4b800000, v69
	v_cndmask_b32_e32 v69, v69, v70, vcc
	v_rsq_f32_e32 v68, v68
	v_rsq_f32_e32 v69, v69
	s_nop 0
	v_pk_mul_f32 v[70:71], v[68:69], s[20:21] op_sel_hi:[1,0]
	s_nop 0
	v_cndmask_b32_e32 v101, v69, v71, vcc
	v_cndmask_b32_e64 v100, v68, v70, s[0:1]
	global_load_dwordx4 v[68:71], v[102:103], off offset:112
	global_load_dwordx4 v[72:75], v[102:103], off offset:48
	global_load_dwordx4 v[76:79], v[102:103], off offset:96
	global_load_dwordx4 v[80:83], v[102:103], off offset:32
	global_load_dwordx4 v[84:87], v[102:103], off offset:80
	global_load_dwordx4 v[88:91], v[102:103], off offset:16
	global_load_dwordx4 v[92:95], v[102:103], off offset:64
	s_nop 0
	global_load_dwordx4 v[102:105], v[102:103], off
	v_pk_mul_f32 v[64:65], v[64:65], v[100:101]
	v_pk_mul_f32 v[52:53], v[52:53], v[100:101]
	v_cvt_pk_bf16_f32 v64, v64, v65
	v_cvt_pk_bf16_f32 v52, v52, v53
	v_pk_mul_f32 v[60:61], v[60:61], v[100:101]
	v_pk_mul_f32 v[56:57], v[56:57], v[100:101]
	v_cvt_pk_bf16_f32 v60, v60, v61
	v_cvt_pk_bf16_f32 v56, v56, v57
	s_waitcnt vmcnt(1)
; DI unsigned pack2(float a, float b) { f32x2_t v = {a, b}; return __builtin_bit_cast(unsigned, __builtin_convertvector(v, bf16x2_t)); }
; DI float rowscale(const float* ss, int R) {
;   const float4* q = (const float4*)(ss + (size_t)R * 16);
;   float4 a = q[0], b = q[1], c = q[2], d = q[3];
;   float t = ((a.x + a.y) + (a.z + a.w)) + ((b.x + b.y) + (b.z + b.w)) + ((c.x + c.y) + (c.z + c.w)) + ((d.x + d.y) + (d.z + d.w));
;   return rsqrtf(t * (1.f / 1024.f) + 1e-6f);
; }
; template <int MODE, bool SWAP, int MT>
; DI void gemm_tile(const int wv_, const Params& p, const u16* __restrict__ A, const u16* __restrict__ Bt, int brow, int bcol, char* smem, const float* gnext) {
;     ...
; #pragma unroll
;     for (int m = 0; m < MT; ++m) {
;       int R = brow + wr * (16 * MT) + m * 16 + fq * 4;
;       int b = R / P, pos = R - b * P;
;       const float rs0 = rowscale(p.ss, R), rs1 = rowscale(p.ss, R + 1), rs2 = rowscale(p.ss, R + 2), rs3 = rowscale(p.ss, R + 3);
; #pragma unroll
;       for (int n = 0; n < 4; ++n) {
;         int col = bcol + wc * 64 + n * 16 + fr - 2560;
;         uint2 o; o.x = pack2(acc[m][n][0] * rs0, acc[m][n][1] * rs1); o.y = pack2(acc[m][n][2] * rs2, acc[m][n][3] * rs3);
;         *(uint2*)(p.vt + ((size_t)(b * 512 + col)) * P + pos) = o;
;       }
;     }
	v_mov_b32_e32 v107, v92
	s_waitcnt vmcnt(0)
	v_mov_b32_e32 v106, v102
	v_mov_b32_e32 v92, v103
	v_mov_b32_e32 v102, v104
	v_mov_b32_e32 v103, v94
	v_mov_b32_e32 v94, v105
	v_pk_add_f32 v[92:93], v[106:107], v[92:93]
	v_pk_add_f32 v[94:95], v[102:103], v[94:95]
	s_nop 0
	v_pk_add_f32 v[92:93], v[92:93], v[94:95]
	v_mov_b32_e32 v94, v88
	v_mov_b32_e32 v95, v84
	v_mov_b32_e32 v84, v89
	v_mov_b32_e32 v88, v90
	v_mov_b32_e32 v89, v86
	v_mov_b32_e32 v86, v91
	v_pk_add_f32 v[84:85], v[94:95], v[84:85]
	v_pk_add_f32 v[86:87], v[88:89], v[86:87]
	s_nop 0
	v_pk_add_f32 v[84:85], v[84:85], v[86:87]
	v_mov_b32_e32 v86, v80
	v_mov_b32_e32 v87, v76
	v_mov_b32_e32 v76, v81
	v_mov_b32_e32 v80, v82
	v_mov_b32_e32 v81, v78
	v_mov_b32_e32 v78, v83
	v_pk_add_f32 v[76:77], v[86:87], v[76:77]
	v_pk_add_f32 v[78:79], v[80:81], v[78:79]
	v_pk_add_f32 v[84:85], v[92:93], v[84:85]
	v_pk_add_f32 v[76:77], v[76:77], v[78:79]
	v_mov_b32_e32 v78, v72
	v_mov_b32_e32 v79, v68
	v_mov_b32_e32 v68, v73
	v_mov_b32_e32 v72, v74
	v_mov_b32_e32 v73, v70
	v_mov_b32_e32 v70, v75
	v_pk_add_f32 v[68:69], v[78:79], v[68:69]
	v_pk_add_f32 v[70:71], v[72:73], v[70:71]
	v_pk_add_f32 v[76:77], v[84:85], v[76:77]
	v_pk_add_f32 v[68:69], v[68:69], v[70:71]
	v_mov_b64_e32 v[84:85], s[72:73]
	v_pk_add_f32 v[68:69], v[76:77], v[68:69]
	s_nop 0
	v_pk_fma_f32 v[68:69], v[68:69], s[18:19], v[0:1] op_sel_hi:[1,0,0]
	s_nop 0
	v_mul_f32_e32 v65, 0x4b800000, v68
	v_cmp_gt_f32_e64 s[0:1], s96, v68
	v_cmp_gt_f32_e32 vcc, s96, v69
	s_nop 0
	v_cndmask_b32_e64 v65, v68, v65, s[0:1]
	v_rsq_f32_e32 v68, v65
	v_mul_f32_e32 v65, 0x4b800000, v69
	v_cndmask_b32_e32 v65, v69, v65, vcc
	v_rsq_f32_e32 v69, v65
	s_nop 0
	v_pk_mul_f32 v[70:71], v[68:69], s[20:21] op_sel_hi:[1,0]
	s_nop 0
	v_cndmask_b32_e32 v69, v69, v71, vcc
	v_cndmask_b32_e64 v68, v68, v70, s[0:1]
	v_pk_mul_f32 v[54:55], v[54:55], v[68:69]
	s_movk_i32 s21, 0x4100
	v_cvt_pk_bf16_f32 v53, v54, v55
	v_or_b32_e32 v54, 48, v97
	v_lshlrev_b64 v[70:71], 1, v[98:99]
	v_mad_i64_i32 v[54:55], s[0:1], v54, s21, v[84:85]
	v_lshl_add_u64 v[54:55], v[54:55], 0, v[70:71]
	global_store_dwordx2 v[54:55], v[52:53], off
	v_or_b32_e32 v52, 16, v96
	v_mul_hi_i32 v53, v52, s15
	v_lshrrev_b32_e32 v54, 31, v53
	v_ashrrev_i32_e32 v53, 12, v53
	v_pk_mul_f32 v[62:63], v[62:63], v[68:69]
	v_pk_mul_f32 v[58:59], v[58:59], v[68:69]
	v_add_u32_e32 v54, v53, v54
	v_ashrrev_i32_e32 v53, 31, v52
	v_pk_mul_f32 v[66:67], v[66:67], v[68:69]
	v_cvt_pk_bf16_f32 v61, v62, v63
	v_or_b32_e32 v62, 16, v97
	v_cvt_pk_bf16_f32 v57, v58, v59
	v_or_b32_e32 v58, 32, v97
	v_mad_i32_i24 v86, v54, s19, v52
	v_lshlrev_b64 v[52:53], 6, v[52:53]
	v_cvt_pk_bf16_f32 v65, v66, v67
	v_mad_i64_i32 v[66:67], s[0:1], v97, s21, v[84:85]
	v_mad_i64_i32 v[62:63], s[0:1], v62, s21, v[84:85]
	v_mad_i64_i32 v[58:59], s[0:1], v58, s21, v[84:85]
	v_lshl_add_u64 v[82:83], s[90:91], 0, v[52:53]
	v_or_b32_e32 v52, 18, v96
	v_lshl_add_u64 v[66:67], v[66:67], 0, v[70:71]
	v_lshl_add_u64 v[62:63], v[62:63], 0, v[70:71]
	v_lshl_add_u64 v[58:59], v[58:59], 0, v[70:71]
	v_ashrrev_i32_e32 v53, 31, v52
	global_store_dwordx2 v[66:67], v[64:65], off
	global_store_dwordx2 v[62:63], v[60:61], off
	global_store_dwordx2 v[58:59], v[56:57], off
	v_lshlrev_b64 v[52:53], 6, v[52:53]
	v_lshl_add_u64 v[80:81], s[90:91], 0, v[52:53]
	v_lshl_or_b32 v90, v54, 9, v2
	global_load_dwordx4 v[52:55], v[82:83], off offset:112
	global_load_dwordx4 v[56:59], v[82:83], off offset:48
	global_load_dwordx4 v[60:63], v[82:83], off offset:96
	global_load_dwordx4 v[64:67], v[82:83], off offset:32
	global_load_dwordx4 v[68:71], v[82:83], off offset:80
	global_load_dwordx4 v[72:75], v[82:83], off offset:16
	global_load_dwordx4 v[76:79], v[82:83], off offset:64
	global_load_dwordx4 v[92:95], v[82:83], off
	v_ashrrev_i32_e32 v87, 31, v86
	s_waitcnt vmcnt(1)
	v_mov_b32_e32 v83, v76
	s_waitcnt vmcnt(0)
	v_mov_b32_e32 v82, v92
	v_mov_b32_e32 v76, v93
	v_pk_add_f32 v[76:77], v[82:83], v[76:77]
	v_mov_b32_e32 v82, v94
	v_mov_b32_e32 v83, v78
	v_mov_b32_e32 v78, v95
	v_pk_add_f32 v[78:79], v[82:83], v[78:79]
	s_nop 0
	v_pk_add_f32 v[76:77], v[76:77], v[78:79]
	v_mov_b32_e32 v78, v72
	v_mov_b32_e32 v79, v68
	v_mov_b32_e32 v68, v73
	v_mov_b32_e32 v72, v74
	v_mov_b32_e32 v73, v70
	v_mov_b32_e32 v70, v75
	v_pk_add_f32 v[68:69], v[78:79], v[68:69]
	v_pk_add_f32 v[70:71], v[72:73], v[70:71]
	s_nop 0
	v_pk_add_f32 v[68:69], v[68:69], v[70:71]
	v_mov_b32_e32 v70, v64
	v_mov_b32_e32 v71, v60
	v_mov_b32_e32 v60, v65
	v_mov_b32_e32 v64, v66
	v_mov_b32_e32 v65, v62
	v_mov_b32_e32 v62, v67
	v_pk_add_f32 v[60:61], v[70:71], v[60:61]
	v_pk_add_f32 v[62:63], v[64:65], v[62:63]
	v_pk_add_f32 v[68:69], v[76:77], v[68:69]
	v_pk_add_f32 v[60:61], v[60:61], v[62:63]
	v_mov_b32_e32 v62, v56
	v_mov_b32_e32 v63, v52
	v_mov_b32_e32 v52, v57
	v_mov_b32_e32 v56, v58
	v_mov_b32_e32 v57, v54
	v_mov_b32_e32 v54, v59
	v_pk_add_f32 v[52:53], v[62:63], v[52:53]
	v_pk_add_f32 v[54:55], v[56:57], v[54:55]
	v_pk_add_f32 v[60:61], v[68:69], v[60:61]
	v_pk_add_f32 v[52:53], v[52:53], v[54:55]
	s_nop 0
	v_pk_add_f32 v[52:53], v[60:61], v[52:53]
	s_nop 0
	v_pk_fma_f32 v[52:53], v[52:53], s[18:19], v[0:1] op_sel_hi:[1,0,0]
	s_nop 0
	v_mul_f32_e32 v54, 0x4b800000, v52
	v_cmp_gt_f32_e64 s[0:1], s96, v52
	v_cmp_gt_f32_e32 vcc, s96, v53
	s_nop 0
	v_cndmask_b32_e64 v52, v52, v54, s[0:1]
	v_mul_f32_e32 v54, 0x4b800000, v53
	v_cndmask_b32_e32 v53, v53, v54, vcc
	v_rsq_f32_e32 v52, v52
	v_rsq_f32_e32 v53, v53
	s_nop 0
	v_pk_mul_f32 v[54:55], v[52:53], s[20:21] op_sel_hi:[1,0]
	s_nop 0
	v_cndmask_b32_e32 v89, v53, v55, vcc
	v_cndmask_b32_e64 v88, v52, v54, s[0:1]
	global_load_dwordx4 v[52:55], v[80:81], off offset:112
	global_load_dwordx4 v[56:59], v[80:81], off offset:48
	global_load_dwordx4 v[60:63], v[80:81], off offset:96
	global_load_dwordx4 v[64:67], v[80:81], off offset:32
	global_load_dwordx4 v[68:71], v[80:81], off offset:80
	global_load_dwordx4 v[72:75], v[80:81], off offset:16
	global_load_dwordx4 v[76:79], v[80:81], off offset:64
	s_nop 0
	global_load_dwordx4 v[80:83], v[80:81], off
	v_pk_mul_f32 v[48:49], v[48:49], v[88:89]
	v_pk_mul_f32 v[36:37], v[36:37], v[88:89]
	v_cvt_pk_bf16_f32 v48, v48, v49
	v_cvt_pk_bf16_f32 v36, v36, v37
	v_pk_mul_f32 v[44:45], v[44:45], v[88:89]
	v_pk_mul_f32 v[40:41], v[40:41], v[88:89]
	v_cvt_pk_bf16_f32 v44, v44, v45
	v_cvt_pk_bf16_f32 v40, v40, v41
	s_waitcnt vmcnt(1)
; DI unsigned pack2(float a, float b) { f32x2_t v = {a, b}; return __builtin_bit_cast(unsigned, __builtin_convertvector(v, bf16x2_t)); }
; DI float rowscale(const float* ss, int R) {
;   const float4* q = (const float4*)(ss + (size_t)R * 16);
;   float4 a = q[0], b = q[1], c = q[2], d = q[3];
;   float t = ((a.x + a.y) + (a.z + a.w)) + ((b.x + b.y) + (b.z + b.w)) + ((c.x + c.y) + (c.z + c.w)) + ((d.x + d.y) + (d.z + d.w));
;   return rsqrtf(t * (1.f / 1024.f) + 1e-6f);
; }
; template <int MODE, bool SWAP, int MT>
; DI void gemm_tile(const int wv_, const Params& p, const u16* __restrict__ A, const u16* __restrict__ Bt, int brow, int bcol, char* smem, const float* gnext) {
;     ...
; #pragma unroll
;     for (int m = 0; m < MT; ++m) {
;       int R = brow + wr * (16 * MT) + m * 16 + fq * 4;
;       int b = R / P, pos = R - b * P;
;       const float rs0 = rowscale(p.ss, R), rs1 = rowscale(p.ss, R + 1), rs2 = rowscale(p.ss, R + 2), rs3 = rowscale(p.ss, R + 3);
; #pragma unroll
;       for (int n = 0; n < 4; ++n) {
;         int col = bcol + wc * 64 + n * 16 + fr - 2560;
;         uint2 o; o.x = pack2(acc[m][n][0] * rs0, acc[m][n][1] * rs1); o.y = pack2(acc[m][n][2] * rs2, acc[m][n][3] * rs3);
;         *(uint2*)(p.vt + ((size_t)(b * 512 + col)) * P + pos) = o;
;       }
;     }
	v_mov_b32_e32 v93, v76
	s_waitcnt vmcnt(0)
	v_mov_b32_e32 v92, v80
	v_mov_b32_e32 v76, v81
	v_mov_b32_e32 v80, v82
	v_mov_b32_e32 v81, v78
	v_mov_b32_e32 v78, v83
	v_pk_add_f32 v[76:77], v[92:93], v[76:77]
	v_pk_add_f32 v[78:79], v[80:81], v[78:79]
	s_nop 0
	v_pk_add_f32 v[76:77], v[76:77], v[78:79]
	v_mov_b32_e32 v78, v72
	v_mov_b32_e32 v79, v68
	v_mov_b32_e32 v68, v73
	v_mov_b32_e32 v72, v74
	v_mov_b32_e32 v73, v70
	v_mov_b32_e32 v70, v75
	v_pk_add_f32 v[68:69], v[78:79], v[68:69]
	v_pk_add_f32 v[70:71], v[72:73], v[70:71]
	s_nop 0
	v_pk_add_f32 v[68:69], v[68:69], v[70:71]
	v_mov_b32_e32 v70, v64
	v_mov_b32_e32 v71, v60
	v_mov_b32_e32 v60, v65
	v_mov_b32_e32 v64, v66
	v_mov_b32_e32 v65, v62
	v_mov_b32_e32 v62, v67
	v_pk_add_f32 v[60:61], v[70:71], v[60:61]
	v_pk_add_f32 v[62:63], v[64:65], v[62:63]
	v_pk_add_f32 v[68:69], v[76:77], v[68:69]
	v_pk_add_f32 v[60:61], v[60:61], v[62:63]
	v_mov_b32_e32 v62, v56
	v_mov_b32_e32 v63, v52
	v_mov_b32_e32 v52, v57
	v_mov_b32_e32 v56, v58
	v_mov_b32_e32 v57, v54
	v_mov_b32_e32 v54, v59
	v_pk_add_f32 v[52:53], v[62:63], v[52:53]
	v_pk_add_f32 v[54:55], v[56:57], v[54:55]
	v_pk_add_f32 v[60:61], v[68:69], v[60:61]
	v_pk_add_f32 v[52:53], v[52:53], v[54:55]
	s_nop 0
	v_pk_add_f32 v[52:53], v[60:61], v[52:53]
	s_nop 0
	v_pk_fma_f32 v[52:53], v[52:53], s[18:19], v[0:1] op_sel_hi:[1,0,0]
	s_nop 0
	v_mul_f32_e32 v49, 0x4b800000, v52
	v_cmp_gt_f32_e64 s[0:1], s96, v52
	v_cmp_gt_f32_e32 vcc, s96, v53
	s_nop 0
	v_cndmask_b32_e64 v49, v52, v49, s[0:1]
	v_rsq_f32_e32 v52, v49
	v_mul_f32_e32 v49, 0x4b800000, v53
	v_cndmask_b32_e32 v49, v53, v49, vcc
	v_rsq_f32_e32 v53, v49
	s_nop 0
	v_pk_mul_f32 v[54:55], v[52:53], s[20:21] op_sel_hi:[1,0]
	s_nop 0
	v_cndmask_b32_e32 v53, v53, v55, vcc
	v_cndmask_b32_e64 v52, v52, v54, s[0:1]
	v_pk_mul_f32 v[38:39], v[38:39], v[52:53]
	v_lshlrev_b64 v[54:55], 1, v[86:87]
	v_cvt_pk_bf16_f32 v37, v38, v39
	v_or_b32_e32 v38, 48, v90
	v_mad_i64_i32 v[38:39], s[0:1], v38, s21, v[84:85]
	v_lshl_add_u64 v[38:39], v[38:39], 0, v[54:55]
	global_store_dwordx2 v[38:39], v[36:37], off
	v_or_b32_e32 v36, 32, v96
	v_mul_hi_i32 v37, v36, s15
	v_lshrrev_b32_e32 v38, 31, v37
	v_ashrrev_i32_e32 v37, 12, v37
	v_pk_mul_f32 v[46:47], v[46:47], v[52:53]
	v_pk_mul_f32 v[42:43], v[42:43], v[52:53]
	v_add_u32_e32 v38, v37, v38
	v_ashrrev_i32_e32 v37, 31, v36
	v_pk_mul_f32 v[50:51], v[50:51], v[52:53]
	v_cvt_pk_bf16_f32 v45, v46, v47
	v_or_b32_e32 v46, 16, v90
	v_cvt_pk_bf16_f32 v41, v42, v43
	v_or_b32_e32 v42, 32, v90
	v_mad_i32_i24 v68, v38, s19, v36
	v_lshlrev_b64 v[36:37], 6, v[36:37]
	v_cvt_pk_bf16_f32 v49, v50, v51
	v_mad_i64_i32 v[50:51], s[0:1], v90, s21, v[84:85]
	v_mad_i64_i32 v[46:47], s[0:1], v46, s21, v[84:85]
	v_mad_i64_i32 v[42:43], s[0:1], v42, s21, v[84:85]
	v_lshl_add_u64 v[66:67], s[90:91], 0, v[36:37]
	v_or_b32_e32 v36, 34, v96
	v_lshl_add_u64 v[50:51], v[50:51], 0, v[54:55]
	v_lshl_add_u64 v[46:47], v[46:47], 0, v[54:55]
	v_lshl_add_u64 v[42:43], v[42:43], 0, v[54:55]
	v_ashrrev_i32_e32 v37, 31, v36
	global_store_dwordx2 v[50:51], v[48:49], off
	global_store_dwordx2 v[46:47], v[44:45], off
	global_store_dwordx2 v[42:43], v[40:41], off
	v_lshlrev_b64 v[36:37], 6, v[36:37]
	v_lshl_add_u64 v[64:65], s[90:91], 0, v[36:37]
	v_lshl_or_b32 v72, v38, 9, v2
	global_load_dwordx4 v[36:39], v[66:67], off offset:112
	global_load_dwordx4 v[40:43], v[66:67], off offset:48
	global_load_dwordx4 v[44:47], v[66:67], off offset:96
	global_load_dwordx4 v[48:51], v[66:67], off offset:32
	global_load_dwordx4 v[52:55], v[66:67], off offset:80
	global_load_dwordx4 v[56:59], v[66:67], off offset:16
	global_load_dwordx4 v[60:63], v[66:67], off offset:64
	global_load_dwordx4 v[74:77], v[66:67], off
	v_ashrrev_i32_e32 v69, 31, v68
	s_waitcnt vmcnt(1)
	v_mov_b32_e32 v67, v60
	s_waitcnt vmcnt(0)
	v_mov_b32_e32 v66, v74
	v_mov_b32_e32 v60, v75
	v_pk_add_f32 v[60:61], v[66:67], v[60:61]
	v_mov_b32_e32 v66, v76
	v_mov_b32_e32 v67, v62
	v_mov_b32_e32 v62, v77
	v_pk_add_f32 v[62:63], v[66:67], v[62:63]
	s_nop 0
	v_pk_add_f32 v[60:61], v[60:61], v[62:63]
	v_mov_b32_e32 v62, v56
	v_mov_b32_e32 v63, v52
	v_mov_b32_e32 v52, v57
	v_mov_b32_e32 v56, v58
	v_mov_b32_e32 v57, v54
	v_mov_b32_e32 v54, v59
	v_pk_add_f32 v[52:53], v[62:63], v[52:53]
	v_pk_add_f32 v[54:55], v[56:57], v[54:55]
	s_nop 0
	v_pk_add_f32 v[52:53], v[52:53], v[54:55]
	v_mov_b32_e32 v54, v48
	v_mov_b32_e32 v55, v44
	v_mov_b32_e32 v44, v49
	v_mov_b32_e32 v48, v50
	v_mov_b32_e32 v49, v46
	v_mov_b32_e32 v46, v51
	v_pk_add_f32 v[44:45], v[54:55], v[44:45]
	v_pk_add_f32 v[46:47], v[48:49], v[46:47]
	v_pk_add_f32 v[52:53], v[60:61], v[52:53]
	v_pk_add_f32 v[44:45], v[44:45], v[46:47]
	v_mov_b32_e32 v46, v40
	v_mov_b32_e32 v47, v36
	v_mov_b32_e32 v36, v41
	v_mov_b32_e32 v40, v42
	v_mov_b32_e32 v41, v38
	v_mov_b32_e32 v38, v43
	v_pk_add_f32 v[36:37], v[46:47], v[36:37]
	v_pk_add_f32 v[38:39], v[40:41], v[38:39]
	v_pk_add_f32 v[44:45], v[52:53], v[44:45]
	v_pk_add_f32 v[36:37], v[36:37], v[38:39]
	s_nop 0
	v_pk_add_f32 v[36:37], v[44:45], v[36:37]
	s_nop 0
	v_pk_fma_f32 v[36:37], v[36:37], s[18:19], v[0:1] op_sel_hi:[1,0,0]
	s_nop 0
	v_mul_f32_e32 v38, 0x4b800000, v36
	v_cmp_gt_f32_e64 s[0:1], s96, v36
	v_cmp_gt_f32_e32 vcc, s96, v37
	s_nop 0
	v_cndmask_b32_e64 v36, v36, v38, s[0:1]
	v_mul_f32_e32 v38, 0x4b800000, v37
	v_cndmask_b32_e32 v37, v37, v38, vcc
	v_rsq_f32_e32 v36, v36
	v_rsq_f32_e32 v37, v37
	s_nop 0
	v_pk_mul_f32 v[38:39], v[36:37], s[20:21] op_sel_hi:[1,0]
	s_nop 0
	v_cndmask_b32_e32 v71, v37, v39, vcc
	v_cndmask_b32_e64 v70, v36, v38, s[0:1]
	global_load_dwordx4 v[36:39], v[64:65], off offset:112
	global_load_dwordx4 v[40:43], v[64:65], off offset:48
	global_load_dwordx4 v[44:47], v[64:65], off offset:96
	global_load_dwordx4 v[48:51], v[64:65], off offset:32
	global_load_dwordx4 v[52:55], v[64:65], off offset:80
	global_load_dwordx4 v[56:59], v[64:65], off offset:16
	global_load_dwordx4 v[60:63], v[64:65], off offset:64
	s_nop 0
	global_load_dwordx4 v[64:67], v[64:65], off
	v_pk_mul_f32 v[32:33], v[32:33], v[70:71]
	v_pk_mul_f32 v[20:21], v[20:21], v[70:71]
	v_cvt_pk_bf16_f32 v32, v32, v33
	v_cvt_pk_bf16_f32 v20, v20, v21
	v_pk_mul_f32 v[28:29], v[28:29], v[70:71]
	v_pk_mul_f32 v[24:25], v[24:25], v[70:71]
	v_cvt_pk_bf16_f32 v28, v28, v29
	v_cvt_pk_bf16_f32 v24, v24, v25
	s_waitcnt vmcnt(1)
; DI unsigned pack2(float a, float b) { f32x2_t v = {a, b}; return __builtin_bit_cast(unsigned, __builtin_convertvector(v, bf16x2_t)); }
; DI float rowscale(const float* ss, int R) {
;   const float4* q = (const float4*)(ss + (size_t)R * 16);
;   float4 a = q[0], b = q[1], c = q[2], d = q[3];
;   float t = ((a.x + a.y) + (a.z + a.w)) + ((b.x + b.y) + (b.z + b.w)) + ((c.x + c.y) + (c.z + c.w)) + ((d.x + d.y) + (d.z + d.w));
;   return rsqrtf(t * (1.f / 1024.f) + 1e-6f);
; }
; template <int MODE, bool SWAP, int MT>
; DI void gemm_tile(const int wv_, const Params& p, const u16* __restrict__ A, const u16* __restrict__ Bt, int brow, int bcol, char* smem, const float* gnext) {
;     ...
; #pragma unroll
;     for (int m = 0; m < MT; ++m) {
;       int R = brow + wr * (16 * MT) + m * 16 + fq * 4;
;       int b = R / P, pos = R - b * P;
;       const float rs0 = rowscale(p.ss, R), rs1 = rowscale(p.ss, R + 1), rs2 = rowscale(p.ss, R + 2), rs3 = rowscale(p.ss, R + 3);
; #pragma unroll
;       for (int n = 0; n < 4; ++n) {
;         int col = bcol + wc * 64 + n * 16 + fr - 2560;
;         uint2 o; o.x = pack2(acc[m][n][0] * rs0, acc[m][n][1] * rs1); o.y = pack2(acc[m][n][2] * rs2, acc[m][n][3] * rs3);
;         *(uint2*)(p.vt + ((size_t)(b * 512 + col)) * P + pos) = o;
;       }
;     }
	v_mov_b32_e32 v75, v60
	s_waitcnt vmcnt(0)
	v_mov_b32_e32 v74, v64
	v_mov_b32_e32 v60, v65
	v_mov_b32_e32 v64, v66
	v_mov_b32_e32 v65, v62
	v_mov_b32_e32 v62, v67
	v_pk_add_f32 v[60:61], v[74:75], v[60:61]
	v_pk_add_f32 v[62:63], v[64:65], v[62:63]
	s_nop 0
	v_pk_add_f32 v[60:61], v[60:61], v[62:63]
	v_mov_b32_e32 v62, v56
	v_mov_b32_e32 v63, v52
	v_mov_b32_e32 v52, v57
	v_mov_b32_e32 v56, v58
	v_mov_b32_e32 v57, v54
	v_mov_b32_e32 v54, v59
	v_pk_add_f32 v[52:53], v[62:63], v[52:53]
	v_pk_add_f32 v[54:55], v[56:57], v[54:55]
	s_nop 0
	v_pk_add_f32 v[52:53], v[52:53], v[54:55]
	v_mov_b32_e32 v54, v48
	v_mov_b32_e32 v55, v44
	v_mov_b32_e32 v44, v49
	v_mov_b32_e32 v48, v50
	v_mov_b32_e32 v49, v46
	v_mov_b32_e32 v46, v51
	v_pk_add_f32 v[44:45], v[54:55], v[44:45]
	v_pk_add_f32 v[46:47], v[48:49], v[46:47]
	v_pk_add_f32 v[52:53], v[60:61], v[52:53]
	v_pk_add_f32 v[44:45], v[44:45], v[46:47]
	v_mov_b32_e32 v46, v40
	v_mov_b32_e32 v47, v36
	v_mov_b32_e32 v36, v41
	v_mov_b32_e32 v40, v42
	v_mov_b32_e32 v41, v38
	v_mov_b32_e32 v38, v43
	v_pk_add_f32 v[36:37], v[46:47], v[36:37]
	v_pk_add_f32 v[38:39], v[40:41], v[38:39]
	v_pk_add_f32 v[44:45], v[52:53], v[44:45]
	v_pk_add_f32 v[36:37], v[36:37], v[38:39]
	s_nop 0
	v_pk_add_f32 v[36:37], v[44:45], v[36:37]
	s_nop 0
	v_pk_fma_f32 v[36:37], v[36:37], s[18:19], v[0:1] op_sel_hi:[1,0,0]
	s_nop 0
	v_mul_f32_e32 v33, 0x4b800000, v36
	v_cmp_gt_f32_e64 s[0:1], s96, v36
	v_cmp_gt_f32_e32 vcc, s96, v37
	s_nop 0
	v_cndmask_b32_e64 v33, v36, v33, s[0:1]
	v_rsq_f32_e32 v36, v33
	v_mul_f32_e32 v33, 0x4b800000, v37
	v_cndmask_b32_e32 v33, v37, v33, vcc
	v_rsq_f32_e32 v37, v33
	s_nop 0
	v_pk_mul_f32 v[38:39], v[36:37], s[20:21] op_sel_hi:[1,0]
	s_nop 0
	v_cndmask_b32_e32 v37, v37, v39, vcc
	v_cndmask_b32_e64 v36, v36, v38, s[0:1]
	v_pk_mul_f32 v[22:23], v[22:23], v[36:37]
	v_lshlrev_b64 v[38:39], 1, v[68:69]
	v_cvt_pk_bf16_f32 v21, v22, v23
	v_or_b32_e32 v22, 48, v72
	v_mad_i64_i32 v[22:23], s[0:1], v22, s21, v[84:85]
	v_lshl_add_u64 v[22:23], v[22:23], 0, v[38:39]
	global_store_dwordx2 v[22:23], v[20:21], off
	v_or_b32_e32 v20, 48, v96
	v_mul_hi_i32 v21, v20, s15
	v_lshrrev_b32_e32 v22, 31, v21
	v_ashrrev_i32_e32 v21, 12, v21
	v_add_u32_e32 v40, v21, v22
	v_ashrrev_i32_e32 v21, 31, v20
	v_pk_mul_f32 v[30:31], v[30:31], v[36:37]
	v_pk_mul_f32 v[26:27], v[26:27], v[36:37]
	v_mad_i32_i24 v52, v40, s19, v20
	v_lshlrev_b64 v[20:21], 6, v[20:21]
	v_pk_mul_f32 v[34:35], v[34:35], v[36:37]
	v_cvt_pk_bf16_f32 v29, v30, v31
	v_or_b32_e32 v30, 16, v72
	v_cvt_pk_bf16_f32 v25, v26, v27
	v_or_b32_e32 v26, 32, v72
	v_lshl_add_u64 v[48:49], s[90:91], 0, v[20:21]
	v_or_b32_e32 v20, 50, v96
	v_cvt_pk_bf16_f32 v33, v34, v35
	v_mad_i64_i32 v[34:35], s[0:1], v72, s21, v[84:85]
	v_mad_i64_i32 v[30:31], s[0:1], v30, s21, v[84:85]
	v_mad_i64_i32 v[26:27], s[0:1], v26, s21, v[84:85]
	v_ashrrev_i32_e32 v21, 31, v20
	v_lshl_add_u64 v[34:35], v[34:35], 0, v[38:39]
	v_lshl_add_u64 v[30:31], v[30:31], 0, v[38:39]
	v_lshl_add_u64 v[26:27], v[26:27], 0, v[38:39]
	v_lshlrev_b64 v[20:21], 6, v[20:21]
	global_store_dwordx2 v[34:35], v[32:33], off
	global_store_dwordx2 v[30:31], v[28:29], off
	global_store_dwordx2 v[26:27], v[24:25], off
	v_lshl_add_u64 v[32:33], s[90:91], 0, v[20:21]
	global_load_dwordx4 v[20:23], v[32:33], off offset:48
	global_load_dwordx4 v[24:27], v[32:33], off offset:16
	global_load_dwordx4 v[28:31], v[32:33], off
	s_nop 0
	global_load_dwordx4 v[32:35], v[32:33], off offset:32
	v_lshl_or_b32 v2, v40, 9, v2
	v_ashrrev_i32_e32 v53, 31, v52
	s_waitcnt vmcnt(3)
	v_mov_b32_e32 v37, v22
	v_mov_b32_e32 v36, v21
	s_waitcnt vmcnt(1)
	v_mov_b32_e32 v22, v29
	v_pk_add_f32 v[28:29], v[28:29], v[22:23]
	v_mov_b32_e32 v22, v31
	v_pk_add_f32 v[30:31], v[30:31], v[22:23]
	v_mov_b32_e32 v22, v25
	v_mov_b32_e32 v21, v23
	v_pk_add_f32 v[24:25], v[24:25], v[22:23]
	v_mov_b32_e32 v22, v27
	v_pk_add_f32 v[20:21], v[36:37], v[20:21]
	v_pk_add_f32 v[26:27], v[26:27], v[22:23]
	v_pk_add_f32 v[56:57], v[20:21], v[20:21] op_sel:[0,1] op_sel_hi:[1,0]
	v_or_b32_e32 v20, 51, v96
	s_waitcnt vmcnt(0)
	v_mov_b32_e32 v29, v32
	v_mov_b32_e32 v31, v33
	v_mov_b32_e32 v25, v34
	v_mov_b32_e32 v27, v35
	v_ashrrev_i32_e32 v21, 31, v20
	v_pk_add_f32 v[28:29], v[28:29], v[30:31]
	v_pk_add_f32 v[24:25], v[24:25], v[26:27]
	v_lshlrev_b64 v[20:21], 6, v[20:21]
	v_pk_add_f32 v[24:25], v[28:29], v[24:25]
	v_lshl_add_u64 v[32:33], s[90:91], 0, v[20:21]
	v_pk_add_f32 v[54:55], v[24:25], v[24:25] op_sel:[0,1] op_sel_hi:[1,0]
	global_load_dwordx4 v[20:23], v[32:33], off offset:32
	global_load_dwordx4 v[24:27], v[32:33], off offset:16
	global_load_dwordx4 v[28:31], v[32:33], off
	s_nop 0
	global_load_dwordx4 v[32:35], v[32:33], off offset:48
	s_waitcnt vmcnt(2)
	v_mov_b32_e32 v38, v25
	s_waitcnt vmcnt(1)
; DI unsigned pack2(float a, float b) { f32x2_t v = {a, b}; return __builtin_bit_cast(unsigned, __builtin_convertvector(v, bf16x2_t)); }
; DI float rowscale(const float* ss, int R) {
;   const float4* q = (const float4*)(ss + (size_t)R * 16);
;   float4 a = q[0], b = q[1], c = q[2], d = q[3];
;   float t = ((a.x + a.y) + (a.z + a.w)) + ((b.x + b.y) + (b.z + b.w)) + ((c.x + c.y) + (c.z + c.w)) + ((d.x + d.y) + (d.z + d.w));
;   return rsqrtf(t * (1.f / 1024.f) + 1e-6f);
; }
; template <int MODE, bool SWAP, int MT>
; DI void gemm_tile(const int wv_, const Params& p, const u16* __restrict__ A, const u16* __restrict__ Bt, int brow, int bcol, char* smem, const float* gnext) {
;     ...
; #pragma unroll
;     for (int m = 0; m < MT; ++m) {
;       int R = brow + wr * (16 * MT) + m * 16 + fq * 4;
;       int b = R / P, pos = R - b * P;
;       const float rs0 = rowscale(p.ss, R), rs1 = rowscale(p.ss, R + 1), rs2 = rowscale(p.ss, R + 2), rs3 = rowscale(p.ss, R + 3);
; #pragma unroll
;       for (int n = 0; n < 4; ++n) {
;         int col = bcol + wc * 64 + n * 16 + fr - 2560;
;         uint2 o; o.x = pack2(acc[m][n][0] * rs0, acc[m][n][1] * rs1); o.y = pack2(acc[m][n][2] * rs2, acc[m][n][3] * rs3);
;         *(uint2*)(p.vt + ((size_t)(b * 512 + col)) * P + pos) = o;
;       }
;     }
	v_mov_b32_e32 v36, v29
	v_mov_b32_e32 v37, v30
	v_mov_b32_e32 v39, v26
	v_mov_b32_e32 v29, v31
	v_mov_b32_e32 v25, v27
	v_mov_b32_e32 v26, v21
	v_pk_add_f32 v[28:29], v[36:37], v[28:29]
	v_pk_add_f32 v[24:25], v[38:39], v[24:25]
	v_pk_add_f32 v[20:21], v[20:21], v[26:27]
	v_mov_b32_e32 v26, v23
	v_pk_add_f32 v[28:29], v[28:29], v[28:29] op_sel:[0,1] op_sel_hi:[1,0]
	v_pk_add_f32 v[24:25], v[24:25], v[24:25] op_sel:[0,1] op_sel_hi:[1,0]
	v_pk_add_f32 v[22:23], v[22:23], v[26:27]
	s_waitcnt vmcnt(0)
	v_mov_b32_e32 v29, v32
	v_mov_b32_e32 v25, v33
	v_mov_b32_e32 v21, v34
	v_mov_b32_e32 v23, v35
	v_pk_add_f32 v[24:25], v[28:29], v[24:25]
	v_pk_add_f32 v[20:21], v[20:21], v[22:23]
	s_nop 0
	v_pk_add_f32 v[58:59], v[24:25], v[20:21]
	global_load_dwordx4 v[20:23], v[48:49], off offset:112
	global_load_dwordx4 v[24:27], v[48:49], off offset:48
	global_load_dwordx4 v[28:31], v[48:49], off offset:96
	global_load_dwordx4 v[32:35], v[48:49], off offset:32
	global_load_dwordx4 v[36:39], v[48:49], off offset:80
	global_load_dwordx4 v[40:43], v[48:49], off offset:16
	global_load_dwordx4 v[44:47], v[48:49], off offset:64
	s_nop 0
	global_load_dwordx4 v[48:51], v[48:49], off
	v_mov_b32_e32 v55, v58
	v_mov_b32_e32 v57, v59
	s_waitcnt vmcnt(1)
	v_mov_b32_e32 v61, v44
	s_waitcnt vmcnt(0)
	v_mov_b32_e32 v60, v48
	v_mov_b32_e32 v44, v49
	v_mov_b32_e32 v48, v50
	v_mov_b32_e32 v49, v46
	v_mov_b32_e32 v46, v51
	v_pk_add_f32 v[44:45], v[60:61], v[44:45]
	v_pk_add_f32 v[46:47], v[48:49], v[46:47]
	s_nop 0
	v_pk_add_f32 v[44:45], v[44:45], v[46:47]
	v_mov_b32_e32 v46, v40
	v_mov_b32_e32 v47, v36
	v_mov_b32_e32 v36, v41
	v_mov_b32_e32 v40, v42
	v_mov_b32_e32 v41, v38
	v_mov_b32_e32 v38, v43
	v_pk_add_f32 v[36:37], v[46:47], v[36:37]
	v_pk_add_f32 v[38:39], v[40:41], v[38:39]
	s_nop 0
	v_pk_add_f32 v[36:37], v[36:37], v[38:39]
	v_mov_b32_e32 v38, v32
	v_mov_b32_e32 v39, v28
	v_mov_b32_e32 v28, v33
	v_mov_b32_e32 v32, v34
	v_mov_b32_e32 v33, v30
	v_mov_b32_e32 v30, v35
	v_pk_add_f32 v[28:29], v[38:39], v[28:29]
	v_pk_add_f32 v[30:31], v[32:33], v[30:31]
	v_pk_add_f32 v[36:37], v[44:45], v[36:37]
	v_pk_add_f32 v[28:29], v[28:29], v[30:31]
	v_mov_b32_e32 v30, v24
	v_mov_b32_e32 v31, v20
	v_mov_b32_e32 v20, v25
	v_mov_b32_e32 v24, v26
	v_mov_b32_e32 v25, v22
	v_mov_b32_e32 v22, v27
	v_pk_add_f32 v[20:21], v[30:31], v[20:21]
	v_pk_add_f32 v[22:23], v[24:25], v[22:23]
	v_pk_add_f32 v[28:29], v[36:37], v[28:29]
	v_pk_add_f32 v[20:21], v[20:21], v[22:23]
	s_nop 0
	v_pk_add_f32 v[20:21], v[28:29], v[20:21]
	s_nop 0
	v_pk_fma_f32 v[20:21], v[20:21], s[18:19], v[0:1] op_sel_hi:[1,0,0]
	s_nop 0
	v_mul_f32_e32 v22, 0x4b800000, v20
	v_cmp_gt_f32_e64 s[0:1], s96, v20
	v_cmp_gt_f32_e32 vcc, s96, v21
	s_nop 0
	v_cndmask_b32_e64 v20, v20, v22, s[0:1]
	v_mul_f32_e32 v22, 0x4b800000, v21
	v_cndmask_b32_e32 v21, v21, v22, vcc
	v_rsq_f32_e32 v20, v20
	v_rsq_f32_e32 v21, v21
	s_nop 0
	v_pk_mul_f32 v[22:23], v[20:21], s[20:21] op_sel_hi:[1,0]
	s_nop 0
	v_cndmask_b32_e32 v21, v21, v23, vcc
	v_cndmask_b32_e64 v20, v20, v22, s[0:1]
	v_pk_add_f32 v[22:23], v[54:55], v[56:57]
	v_pk_mul_f32 v[16:17], v[16:17], v[20:21]
	v_pk_fma_f32 v[0:1], v[22:23], s[18:19], v[0:1] op_sel_hi:[1,0,0]
	v_cvt_pk_bf16_f32 v16, v16, v17
	v_mul_f32_e32 v17, 0x4b800000, v0
	v_cmp_gt_f32_e64 s[0:1], s96, v0
	v_cmp_gt_f32_e32 vcc, s96, v1
	v_pk_mul_f32 v[8:9], v[8:9], v[20:21]
	v_cndmask_b32_e64 v0, v0, v17, s[0:1]
	v_mul_f32_e32 v17, 0x4b800000, v1
	v_cndmask_b32_e32 v1, v1, v17, vcc
	v_rsq_f32_e32 v0, v0
	v_rsq_f32_e32 v1, v1
	v_cvt_pk_bf16_f32 v8, v8, v9
	v_pk_mul_f32 v[12:13], v[12:13], v[20:21]
	v_pk_mul_f32 v[4:5], v[4:5], v[20:21]
	v_pk_mul_f32 v[22:23], v[0:1], s[20:21] op_sel_hi:[1,0]
	v_cvt_pk_bf16_f32 v12, v12, v13
	v_cndmask_b32_e32 v1, v1, v23, vcc
	v_cndmask_b32_e64 v0, v0, v22, s[0:1]
	v_pk_mul_f32 v[10:11], v[10:11], v[0:1]
	v_lshlrev_b64 v[22:23], 1, v[52:53]
	v_cvt_pk_bf16_f32 v9, v10, v11
	v_or_b32_e32 v10, 32, v2
	v_mad_i64_i32 v[10:11], s[0:1], v10, s21, v[84:85]
	v_pk_mul_f32 v[14:15], v[14:15], v[0:1]
	v_lshl_add_u64 v[10:11], v[10:11], 0, v[22:23]
	v_pk_mul_f32 v[18:19], v[18:19], v[0:1]
	v_cvt_pk_bf16_f32 v13, v14, v15
	v_or_b32_e32 v14, 16, v2
	global_store_dwordx2 v[10:11], v[8:9], off
	v_cvt_pk_bf16_f32 v8, v4, v5
	v_pk_mul_f32 v[4:5], v[6:7], v[0:1]
	v_or_b32_e32 v0, 48, v2
	v_cvt_pk_bf16_f32 v17, v18, v19
	v_mad_i64_i32 v[18:19], s[0:1], v2, s21, v[84:85]
	v_mad_i64_i32 v[14:15], s[0:1], v14, s21, v[84:85]
	v_mad_i64_i32 v[0:1], s[0:1], v0, s21, v[84:85]
	v_lshl_add_u64 v[18:19], v[18:19], 0, v[22:23]
	v_lshl_add_u64 v[14:15], v[14:15], 0, v[22:23]
	v_lshl_add_u64 v[6:7], v[0:1], 0, v[22:23]
	global_store_dwordx2 v[18:19], v[16:17], off
	global_store_dwordx2 v[14:15], v[12:13], off
	global_store_dword v[6:7], v8, off
	s_branch .LBB0_83

; template <int MODE, bool SWAP, int MT>
; DI void gemm_tile(const int wv_, const Params& p, const u16* __restrict__ A, const u16* __restrict__ Bt, int brow, int bcol, char* smem, const float* gnext) {
;     ...
;   for (int t = 0; t < 32; ++t) {
;     asm volatile("s_waitcnt vmcnt(0)" ::: "memory");
;     __syncthreads();
;     if (t + 1 < 32) stage(t + 1, (t + 1) & 1);
;     const char* sA = smem + (t & 1) * 24576; const char* sB = sA + 16384;
;     bf16x8 Af[MT], Bf[4];
; #pragma unroll
;     for (int n = 0; n < 4; ++n) Bf[n] = *(const bf16x8*)(sB + (wc * 64 + n * 16 + fr) * 64 + fq * 16);
;     constexpr int MH = MT >= 2 ? MT / 2 : 1;
; #pragma unroll
;     for (int m = 0; m < MH; ++m) Af[m] = *(const bf16x8*)(sA + (wr * (16 * MT) + m * 16 + fr) * 64 + fq * 16);
;     __builtin_amdgcn_sched_barrier(0);
; #pragma unroll
;     for (int m = MH; m < MT; ++m) Af[m] = *(const bf16x8*)(sA + (wr * (16 * MT) + m * 16 + fr) * 64 + fq * 16);
; #pragma unroll
;     for (int m = 0; m < MH; ++m)
; #pragma unroll
;       for (int n = 0; n < 4; ++n)
;         acc[m][n] = SWAP ? __builtin_amdgcn_mfma_f32_16x16x32_bf16(Bf[n], Af[m], acc[m][n], 0, 0, 0)
;                          : __builtin_amdgcn_mfma_f32_16x16x32_bf16(Af[m], Bf[n], acc[m][n], 0, 0, 0);
;     __builtin_amdgcn_sched_barrier(0);
; #pragma unroll
;     for (int m = MH; m < MT; ++m)
; #pragma unroll
;       for (int n = 0; n < 4; ++n)
;         acc[m][n] = SWAP ? __builtin_amdgcn_mfma_f32_16x16x32_bf16(Bf[n], Af[m], acc[m][n], 0, 0, 0)
;                          : __builtin_amdgcn_mfma_f32_16x16x32_bf16(Af[m], Bf[n], acc[m][n], 0, 0, 0);
;     ...
;       } else {
;         const float rs = rowscale(p.ss, R);
; #pragma unroll
;         for (int n = 0; n < 4; ++n) { acc[m][n][0] *= rs; acc[m][n][1] *= rs; acc[m][n][2] *= rs; acc[m][n][3] *= rs; }
;         if (MODE == 0 && bcol >= 512 && bcol < 1536) {
;           int b = R / P, pos = R - b * P;
;           u16* dstb = (bcol < 1024 ? p.kc : p.vc);
; #pragma unroll
;           for (int n = 0; n < 4; ++n) {
;             int cc = (bcol & 511) + wc * 64 + n * 16 + fq * 4;
;             uint2 o; o.x = pack2(acc[m][n][0], acc[m][n][1]); o.y = pack2(acc[m][n][2], acc[m][n][3]);
;             *(uint2*)(dstb + ((size_t)((b * 8 + (cc >> 6)) * P + pos)) * 64 + (cc & 63)) = o;
;           }
;         } else {
;           const int LD = MODE == 0 ? LD_AB : LD_CD;
.Lpp_exit_3:
	s_add_i32 s98, s22, s13
	s_cmp_lt_i32 s98, s14
	s_cselect_b32 s98, s98, s22
	s_mul_hi_u32 s99, s98, 0x3e0f83e1
	s_lshr_b32 s99, s99, 3
	s_mul_i32 s100, s99, 33
	s_sub_i32 s100, s98, s100
	s_lshl_b32 s99, s99, 8
	s_sub_i32 s98, s99, s0
	s_add_i32 s98, s98, -1
	s_ashr_i32 s99, s98, 31
	s_lshl_b64 s[98:99], s[98:99], 11
	s_lshl_b32 s100, s100, 7
	s_sub_i32 s100, s100, s23
	s_add_i32 s100, s100, -1
	s_ashr_i32 s101, s100, 31
	s_lshl_b64 s[100:101], s[100:101], 11
	v_lshl_add_u64 v[112:113], v[0:1], 0, s[98:99]
	v_lshl_add_u64 v[114:115], v[68:69], 0, s[98:99]
	v_lshl_add_u64 v[116:117], v[70:71], 0, s[100:101]
	v_add_u32_e32 v0, v77, v79
	v_add_u32_e32 v1, v77, v78
	s_waitcnt vmcnt(0)
	s_waitcnt vmcnt(0)
	s_barrier
	global_load_dword v108, v[112:113], off
	global_load_dword v109, v[114:115], off
	global_load_dword v110, v[116:117], off
	ds_read_b128 v[68:71], v0 offset:25600
	ds_read_b128 v[80:83], v0 offset:24576
	ds_read_b128 v[76:79], v1 offset:44032
	ds_read_b128 v[84:87], v1 offset:43008
	ds_read_b128 v[88:91], v1 offset:41984
	ds_read_b128 v[92:95], v1 offset:40960
	s_waitcnt lgkmcnt(0)
	v_mfma_f32_16x16x32_bf16 v[64:67], v[92:95], v[80:83], v[64:67]
	v_mfma_f32_16x16x32_bf16 v[60:63], v[88:91], v[80:83], v[60:63]
	v_mfma_f32_16x16x32_bf16 v[56:59], v[84:87], v[80:83], v[56:59]
	v_mfma_f32_16x16x32_bf16 v[52:55], v[76:79], v[80:83], v[52:55]
	ds_read_b128 v[80:83], v0 offset:26624
	ds_read_b128 v[96:99], v0 offset:27648
	v_mfma_f32_16x16x32_bf16 v[48:51], v[92:95], v[68:71], v[48:51]
	v_mfma_f32_16x16x32_bf16 v[40:43], v[88:91], v[68:71], v[40:43]
	v_mfma_f32_16x16x32_bf16 v[36:39], v[84:87], v[68:71], v[36:39]
	v_mfma_f32_16x16x32_bf16 v[44:47], v[76:79], v[68:71], v[44:47]
	v_or_b32_e32 v0, s0, v75
	v_lshl_add_u32 v68, v74, 6, v0
	v_ashrrev_i32_e32 v69, 31, v68
	v_lshlrev_b64 v[70:71], 6, v[68:69]
	v_lshl_add_u64 v[74:75], s[90:91], 0, v[70:71]
	s_waitcnt lgkmcnt(1)
	v_mfma_f32_16x16x32_bf16 v[32:35], v[92:95], v[80:83], v[32:35]
	s_waitcnt lgkmcnt(0)
	s_barrier
	v_mfma_f32_16x16x32_bf16 v[28:31], v[88:91], v[80:83], v[28:31]
	v_lshlrev_b32_e32 v2, 2, v73
	s_add_i32 s0, s23, 0xfffffe00
	s_cmpk_gt_u32 s0, 0x3ff
	v_mfma_f32_16x16x32_bf16 v[24:27], v[84:87], v[80:83], v[24:27]
	s_cselect_b64 s[8:9], -1, 0
	s_cmpk_lt_u32 s23, 0x400
	s_movk_i32 s0, 0x1058
	v_mfma_f32_16x16x32_bf16 v[20:23], v[76:79], v[80:83], v[20:23]
	s_cselect_b64 s[6:7], -1, 0
	s_mov_b64 s[10:11], -1
	v_mfma_f32_16x16x32_bf16 v[12:15], v[88:91], v[96:99], v[12:15]
	v_mfma_f32_16x16x32_bf16 v[8:11], v[84:87], v[96:99], v[8:11]
	v_mfma_f32_16x16x32_bf16 v[4:7], v[76:79], v[96:99], v[4:7]
	v_lshlrev_b32_e32 v77, 6, v72
	global_load_dwordx4 v[70:73], v[74:75], off offset:32
	global_load_dwordx4 v[78:81], v[74:75], off offset:16
	global_load_dwordx4 v[82:85], v[74:75], off
	global_load_dwordx4 v[86:89], v[74:75], off offset:48
	v_or_b32_e32 v76, s23, v77
	v_mfma_f32_16x16x32_bf16 v[16:19], v[92:95], v[96:99], v[16:19]
	v_or_b32_e32 v0, v76, v2
	v_cmp_gt_i32_e64 s[0:1], s0, v0
	s_waitcnt vmcnt(2)
	v_mov_b32_e32 v90, v79
	s_waitcnt vmcnt(1)
	v_mov_b32_e32 v74, v83
	v_mov_b32_e32 v75, v84
	v_mov_b32_e32 v91, v80
	v_mov_b32_e32 v83, v85
	v_mov_b32_e32 v79, v81
	v_mov_b32_e32 v80, v71
	v_pk_add_f32 v[74:75], v[74:75], v[82:83]
	v_pk_add_f32 v[78:79], v[90:91], v[78:79]
	v_pk_add_f32 v[70:71], v[70:71], v[80:81]
	v_mov_b32_e32 v80, v73
	v_pk_add_f32 v[74:75], v[74:75], v[74:75] op_sel:[0,1] op_sel_hi:[1,0]
	v_pk_add_f32 v[78:79], v[78:79], v[78:79] op_sel:[0,1] op_sel_hi:[1,0]
	v_pk_add_f32 v[72:73], v[72:73], v[80:81]
	s_waitcnt vmcnt(0)
	v_mov_b32_e32 v75, v86
	v_mov_b32_e32 v79, v87
	v_mov_b32_e32 v71, v88
	v_mov_b32_e32 v73, v89
	v_pk_add_f32 v[74:75], v[74:75], v[78:79]
	v_pk_add_f32 v[70:71], v[70:71], v[72:73]
	s_nop 0
	v_pk_add_f32 v[70:71], v[74:75], v[70:71]
	s_nop 0
	v_add_f32_e32 v1, v70, v71
	v_mov_b32_e32 v70, 0x358637bd
	v_fmamk_f32 v1, v1, 0x3a800000, v70
	v_cmp_gt_f32_e32 vcc, s96, v1
	v_mul_f32_e32 v70, 0x4b800000, v1
	s_nop 0
	v_cndmask_b32_e32 v1, v1, v70, vcc
	v_rsq_f32_e32 v1, v1
	s_nop 0
	v_mul_f32_e32 v70, 0x45800000, v1
	v_cndmask_b32_e32 v72, v1, v70, vcc
	v_pk_mul_f32 v[70:71], v[64:65], v[72:73] op_sel_hi:[1,0]
	v_pk_mul_f32 v[66:67], v[66:67], v[72:73] op_sel_hi:[1,0]
	v_pk_mul_f32 v[64:65], v[60:61], v[72:73] op_sel_hi:[1,0]
	v_pk_mul_f32 v[62:63], v[62:63], v[72:73] op_sel_hi:[1,0]
	v_pk_mul_f32 v[60:61], v[56:57], v[72:73] op_sel_hi:[1,0]
	v_pk_mul_f32 v[58:59], v[58:59], v[72:73] op_sel_hi:[1,0]
	v_pk_mul_f32 v[56:57], v[52:53], v[72:73] op_sel_hi:[1,0]
	v_pk_mul_f32 v[52:53], v[54:55], v[72:73] op_sel_hi:[1,0]
	s_and_b64 vcc, exec, s[8:9]
	s_cbranch_vccz .LBB0_388
	v_mov_b64_e32 v[54:55], s[68:69]
	v_mad_i64_i32 v[72:73], s[10:11], v68, s35, v[54:55]
	v_lshlrev_b64 v[54:55], 7, v[68:69]
	s_and_saveexec_b64 s[10:11], s[0:1]
	s_cbranch_execz .LBB0_378
	s_movk_i32 s0, 0x5ff
	v_add_u32_e32 v1, 0xfffffc00, v0
	v_cmp_lt_i32_e32 vcc, s0, v0
	s_movk_i32 s0, 0xa00
	v_cvt_pk_bf16_f32 v74, v70, v71
	v_cndmask_b32_e32 v78, v0, v1, vcc
	v_ashrrev_i32_e32 v79, 31, v78
	v_cvt_pk_bf16_f32 v75, v66, v67
	v_lshl_add_u64 v[78:79], v[78:79], 1, v[72:73]
	v_cmp_eq_u32_e32 vcc, s0, v76
	global_store_dwordx2 v[78:79], v[74:75], off
	s_and_b64 exec, exec, vcc
	s_cbranch_execz .LBB0_378
	v_lshl_add_u64 v[78:79], s[78:79], 0, v[54:55]
	v_mov_b32_e32 v1, v3
	v_lshl_add_u64 v[78:79], v[0:1], 1, v[78:79]
	v_add_co_u32_e32 v78, vcc, 0xfffff000, v78
	s_nop 1
	v_addc_co_u32_e32 v79, vcc, -1, v79, vcc
	global_store_dwordx2 v[78:79], v[74:75], off offset:-1024

; template <int MODE, bool SWAP, int MT>
; DI void gemm_tile(const int wv_, const Params& p, const u16* __restrict__ A, const u16* __restrict__ Bt, int brow, int bcol, char* smem, const float* gnext) {
;     ...
;   for (int t = 0; t < 32; ++t) {
;     asm volatile("s_waitcnt vmcnt(0)" ::: "memory");
;     __syncthreads();
;     if (t + 1 < 32) stage(t + 1, (t + 1) & 1);
;     const char* sA = smem + (t & 1) * 24576; const char* sB = sA + 16384;
;     bf16x8 Af[MT], Bf[4];
; #pragma unroll
;     for (int n = 0; n < 4; ++n) Bf[n] = *(const bf16x8*)(sB + (wc * 64 + n * 16 + fr) * 64 + fq * 16);
;     constexpr int MH = MT >= 2 ? MT / 2 : 1;
; #pragma unroll
;     for (int m = 0; m < MH; ++m) Af[m] = *(const bf16x8*)(sA + (wr * (16 * MT) + m * 16 + fr) * 64 + fq * 16);
;     __builtin_amdgcn_sched_barrier(0);
; #pragma unroll
;     for (int m = MH; m < MT; ++m) Af[m] = *(const bf16x8*)(sA + (wr * (16 * MT) + m * 16 + fr) * 64 + fq * 16);
; #pragma unroll
;     for (int m = 0; m < MH; ++m)
; #pragma unroll
;       for (int n = 0; n < 4; ++n)
;         acc[m][n] = SWAP ? __builtin_amdgcn_mfma_f32_16x16x32_bf16(Bf[n], Af[m], acc[m][n], 0, 0, 0)
;                          : __builtin_amdgcn_mfma_f32_16x16x32_bf16(Af[m], Bf[n], acc[m][n], 0, 0, 0);
;     __builtin_amdgcn_sched_barrier(0);
; #pragma unroll
;     for (int m = MH; m < MT; ++m)
; #pragma unroll
;       for (int n = 0; n < 4; ++n)
;         acc[m][n] = SWAP ? __builtin_amdgcn_mfma_f32_16x16x32_bf16(Bf[n], Af[m], acc[m][n], 0, 0, 0)
;                          : __builtin_amdgcn_mfma_f32_16x16x32_bf16(Af[m], Bf[n], acc[m][n], 0, 0, 0);
;     ...
;       int R = brow + wr * (16 * MT) + m * 16 + fr;
;       if (MODE == 2) {
;         int b = R / P, pos = R - b * P;
;         const bool valid = pos >= 112;
;         float* hr = valid ? hrow(p, b, pos) : nullptr;
;         float ssq = 0.f;
; #pragma unroll
;         for (int n = 0; n < 4; ++n) {
;           int col = bcol + wc * 64 + n * 16 + fq * 4;
;           float4 v = make_float4(0.f, 0.f, 0.f, 0.f);
;           if (valid) {
;             v = *(float4*)(hr + col);
;             v.x += acc[m][n][0]; v.y += acc[m][n][1]; v.z += acc[m][n][2]; v.w += acc[m][n][3];
;             *(float4*)(hr + col) = v;
;           }
.Lpp_exit_4:
	s_add_i32 s98, s28, s20
	s_cmp_lt_i32 s98, s21
	s_cselect_b32 s98, s98, s28
	s_lshr_b32 s99, s98, 3
	s_and_b32 s100, s98, 7
	s_lshl_b32 s99, s99, 8
	s_sub_i32 s98, s99, s0
	s_add_i32 s98, s98, -1
	s_ashr_i32 s99, s98, 31
	s_lshl_b64 s[98:99], s[98:99], 11
	s_lshl_b32 s100, s100, 7
	s_sub_i32 s100, s100, s12
	s_add_i32 s100, s100, -1
	s_ashr_i32 s101, s100, 31
	s_lshl_b64 s[100:101], s[100:101], 11
	v_lshl_add_u64 v[112:113], v[0:1], 0, s[98:99]
	v_lshl_add_u64 v[114:115], v[68:69], 0, s[98:99]
	v_lshl_add_u64 v[116:117], v[70:71], 0, s[100:101]
	v_add_u32_e32 v0, v75, v79
	v_add_u32_e32 v1, v75, v78
	s_waitcnt vmcnt(0)
	s_waitcnt vmcnt(0)
	s_barrier
	global_load_dword v108, v[112:113], off
	global_load_dword v109, v[114:115], off
	global_load_dword v110, v[116:117], off
	ds_read_b128 v[80:83], v0 offset:25600
	ds_read_b128 v[84:87], v0 offset:24576
	ds_read_b128 v[88:91], v1 offset:44032
	ds_read_b128 v[92:95], v1 offset:43008
	ds_read_b128 v[96:99], v1 offset:41984
	ds_read_b128 v[100:103], v1 offset:40960
	s_waitcnt lgkmcnt(0)
	v_mfma_f32_16x16x32_bf16 v[68:71], v[100:103], v[84:87], v[64:67]
	v_mfma_f32_16x16x32_bf16 v[60:63], v[96:99], v[84:87], v[60:63]
	v_mfma_f32_16x16x32_bf16 v[56:59], v[92:95], v[84:87], v[56:59]
	v_mfma_f32_16x16x32_bf16 v[52:55], v[88:91], v[84:87], v[52:55]
	ds_read_b128 v[64:67], v0 offset:26624
	ds_read_b128 v[84:87], v0 offset:27648
	v_mfma_f32_16x16x32_bf16 v[48:51], v[100:103], v[80:83], v[48:51]
	v_mfma_f32_16x16x32_bf16 v[44:47], v[96:99], v[80:83], v[44:47]
	v_mfma_f32_16x16x32_bf16 v[40:43], v[92:95], v[80:83], v[40:43]
	v_mfma_f32_16x16x32_bf16 v[36:39], v[88:91], v[80:83], v[36:39]
	v_or_b32_e32 v0, s0, v73
	v_lshl_add_u32 v72, v72, 6, v0
	s_mov_b32 s0, 0x7e07e07f
	v_mul_hi_i32 v0, v72, s0
	s_waitcnt lgkmcnt(1)
	v_mfma_f32_16x16x32_bf16 v[32:35], v[100:103], v[64:67], v[32:35]
	v_lshrrev_b32_e32 v1, 31, v0
	v_ashrrev_i32_e32 v0, 12, v0
	v_add_u32_e32 v0, v0, v1
	v_mfma_f32_16x16x32_bf16 v[28:31], v[96:99], v[64:67], v[28:31]
	s_movk_i32 s0, 0xdf80
	v_mad_i32_i24 v1, v0, s0, v72
	v_cmp_lt_i32_e64 s[2:3], s54, v1
	v_mfma_f32_16x16x32_bf16 v[24:27], v[92:95], v[64:67], v[24:27]
	v_mov_b64_e32 v[74:75], 0
	s_waitcnt lgkmcnt(0)
	s_barrier
	v_mfma_f32_16x16x32_bf16 v[20:23], v[88:91], v[64:67], v[20:23]
	v_mfma_f32_16x16x32_bf16 v[16:19], v[100:103], v[84:87], v[16:19]
	v_mfma_f32_16x16x32_bf16 v[12:15], v[96:99], v[84:87], v[12:15]
	v_mfma_f32_16x16x32_bf16 v[8:11], v[92:95], v[84:87], v[8:11]
	v_mfma_f32_16x16x32_bf16 v[4:7], v[88:91], v[84:87], v[4:7]
	s_and_saveexec_b64 s[0:1], s[2:3]
	s_cbranch_execz .LBB0_832
	s_movk_i32 s4, 0x7f
	v_cmp_lt_u32_e32 vcc, s4, v1
	v_mov_b32_e32 v64, 0xffffff90
	v_mov_b32_e32 v65, 0xffffff80
	v_cndmask_b32_e64 v2, 4, 13, vcc
	v_cndmask_b32_e32 v66, v64, v65, vcc
	v_lshlrev_b32_e32 v0, v2, v0
	v_mov_b32_e32 v64, s85
	v_mov_b32_e32 v65, s43
	v_add3_u32 v0, v66, v1, v0
	v_cndmask_b32_e32 v65, v64, v65, vcc
	v_mov_b32_e32 v64, s84
	v_mov_b32_e32 v67, s42
	v_ashrrev_i32_e32 v1, 31, v0
	v_cndmask_b32_e32 v64, v64, v67, vcc
	v_lshlrev_b64 v[0:1], 12, v[0:1]
	v_lshl_add_u64 v[74:75], v[64:65], 0, v[0:1]
